# hand-scheduled GEMM epilogues: swiglu (P1 P10) and scale (P3 P7) with all eight rstd rows fetched up front, residual (P2 P6 P9 P11) with pipelined x_old loads; sample rows in 16-row patch blocks; memK
# speedup vs baseline: 1.0374x; 1.0297x over previous
.LBB0_191:
	v_lshrrev_b32_e32 v144, 6, v206
	v_and_b32_e32 v153, 63, v206
	v_lshrrev_b32_e32 v145, 2, v144
	v_and_b32_e32 v144, 3, v144
	v_lshlrev_b32_e32 v145, 6, v145
	v_lshrrev_b32_e32 v210, 4, v153
	v_and_b32_e32 v155, 15, v153
	v_xor_b32_e32 v204, 16, v153
	v_xor_b32_e32 v205, 32, v153
	v_lshlrev_b32_e32 v204, 2, v204
	v_lshlrev_b32_e32 v205, 2, v205
	v_add_u32_e32 v145, v145, v155
	s_lshl_b32 vcc_lo, s28, 8
	v_add_u32_e32 v145, vcc_lo, v145
	v_lshlrev_b32_e32 v153, 5, v144
	v_lshl_add_u32 v153, v210, 3, v153
	s_lshl_b32 vcc_lo, s62, 7
	v_add_u32_e32 v153, vcc_lo, v153
	v_lshlrev_b32_e32 v154, 6, v145
	v_lshl_add_u32 v154, v210, 4, v154
	v_mov_b32_e32 v155, 0x1600
	v_mul_u32_u24_e32 v155, v145, v155
	v_lshl_add_u32 v155, v153, 1, v155
	s_add_u32 s86, s96, 0x4100000
	s_addc_u32 s87, s97, 0
	global_load_dwordx4 v[156:159], v154, s[86:87]
	global_load_dwordx4 v[160:163], v154, s[86:87] offset:1024
	global_load_dwordx4 v[164:167], v154, s[86:87] offset:2048
	global_load_dwordx4 v[168:171], v154, s[86:87] offset:3072
	s_add_u32 s86, s86, 0x2000
	s_addc_u32 s87, s87, 0
	global_load_dwordx4 v[172:175], v154, s[86:87]
	global_load_dwordx4 v[176:179], v154, s[86:87] offset:1024
	global_load_dwordx4 v[180:183], v154, s[86:87] offset:2048
	global_load_dwordx4 v[184:187], v154, s[86:87] offset:3072
	s_add_u32 s88, s96, 0x11f00000
	s_addc_u32 s89, s97, 0
	s_waitcnt vmcnt(7)
	v_add_f32_e32 v156, v156, v157
	v_add_f32_e32 v158, v158, v159
	v_add_f32_e32 v156, v156, v158
	s_waitcnt vmcnt(6)
	v_add_f32_e32 v160, v160, v161
	v_add_f32_e32 v162, v162, v163
	v_add_f32_e32 v160, v160, v162
	s_waitcnt vmcnt(5)
	v_add_f32_e32 v164, v164, v165
	v_add_f32_e32 v166, v166, v167
	v_add_f32_e32 v164, v164, v166
	s_waitcnt vmcnt(4)
	v_add_f32_e32 v168, v168, v169
	v_add_f32_e32 v170, v170, v171
	v_add_f32_e32 v168, v168, v170
	s_waitcnt vmcnt(3)
	v_add_f32_e32 v172, v172, v173
	v_add_f32_e32 v174, v174, v175
	v_add_f32_e32 v172, v172, v174
	s_waitcnt vmcnt(2)
	v_add_f32_e32 v176, v176, v177
	v_add_f32_e32 v178, v178, v179
	v_add_f32_e32 v176, v176, v178
	s_waitcnt vmcnt(1)
	v_add_f32_e32 v180, v180, v181
	v_add_f32_e32 v182, v182, v183
	v_add_f32_e32 v180, v180, v182
	s_waitcnt vmcnt(0)
	v_add_f32_e32 v184, v184, v185
	v_add_f32_e32 v186, v186, v187
	v_add_f32_e32 v184, v184, v186
	ds_bpermute_b32 v157, v204, v156
	ds_bpermute_b32 v161, v204, v160
	ds_bpermute_b32 v165, v204, v164
	ds_bpermute_b32 v169, v204, v168
	ds_bpermute_b32 v173, v204, v172
	ds_bpermute_b32 v177, v204, v176
	ds_bpermute_b32 v181, v204, v180
	ds_bpermute_b32 v185, v204, v184
	s_waitcnt lgkmcnt(0)
	v_add_f32_e32 v156, v156, v157
	v_add_f32_e32 v160, v160, v161
	v_add_f32_e32 v164, v164, v165
	v_add_f32_e32 v168, v168, v169
	v_add_f32_e32 v172, v172, v173
	v_add_f32_e32 v176, v176, v177
	v_add_f32_e32 v180, v180, v181
	v_add_f32_e32 v184, v184, v185
	s_nop 0
	ds_bpermute_b32 v157, v205, v156
	ds_bpermute_b32 v161, v205, v160
	ds_bpermute_b32 v165, v205, v164
	ds_bpermute_b32 v169, v205, v168
	ds_bpermute_b32 v173, v205, v172
	ds_bpermute_b32 v177, v205, v176
	ds_bpermute_b32 v181, v205, v180
	ds_bpermute_b32 v185, v205, v184
	s_waitcnt lgkmcnt(0)
	v_mov_b32_e32 v144, 0x358637bd
	s_mov_b32 vcc_lo, 0x3a800000
	v_add_f32_e32 v156, v156, v157
	v_add_f32_e32 v160, v160, v161
	v_add_f32_e32 v164, v164, v165
	v_add_f32_e32 v168, v168, v169
	v_add_f32_e32 v172, v172, v173
	v_add_f32_e32 v176, v176, v177
	v_add_f32_e32 v180, v180, v181
	v_add_f32_e32 v184, v184, v185
	v_fma_f32 v156, v156, vcc_lo, v144
	v_fma_f32 v160, v160, vcc_lo, v144
	v_fma_f32 v164, v164, vcc_lo, v144
	v_fma_f32 v168, v168, vcc_lo, v144
	v_fma_f32 v172, v172, vcc_lo, v144
	v_fma_f32 v176, v176, vcc_lo, v144
	v_fma_f32 v180, v180, vcc_lo, v144
	v_fma_f32 v184, v184, vcc_lo, v144
	v_rsq_f32_e32 v156, v156
	v_rsq_f32_e32 v160, v160
	v_rsq_f32_e32 v164, v164
	v_rsq_f32_e32 v168, v168
	v_rsq_f32_e32 v172, v172
	v_rsq_f32_e32 v176, v176
	v_rsq_f32_e32 v180, v180
	v_rsq_f32_e32 v184, v184
	s_nop 0
	v_mul_f32_e32 v157, 0xbfb8aa3b, v156
	v_mul_f32_e32 v161, 0xbfb8aa3b, v160
	v_mul_f32_e32 v165, 0xbfb8aa3b, v164
	v_mul_f32_e32 v169, 0xbfb8aa3b, v168
	v_mul_f32_e32 v173, 0xbfb8aa3b, v172
	v_mul_f32_e32 v177, 0xbfb8aa3b, v176
	v_mul_f32_e32 v181, 0xbfb8aa3b, v180
	v_mul_f32_e32 v185, 0xbfb8aa3b, v184
	v_mul_f32_e32 v158, v156, v156
	v_mul_f32_e32 v162, v160, v160
	v_mul_f32_e32 v166, v164, v164
	v_mul_f32_e32 v170, v168, v168
	v_mul_f32_e32 v174, v172, v172
	v_mul_f32_e32 v178, v176, v176
	v_mul_f32_e32 v182, v180, v180
	v_mul_f32_e32 v186, v184, v184
	v_mul_f32_e32 v188, v116, v157
	v_mul_f32_e32 v189, v117, v157
	v_mul_f32_e32 v190, v118, v157
	v_mul_f32_e32 v191, v119, v157
	v_mul_f32_e32 v192, v112, v157
	v_mul_f32_e32 v193, v113, v157
	v_mul_f32_e32 v194, v114, v157
	v_mul_f32_e32 v195, v115, v157
	v_exp_f32_e32 v188, v188
	v_exp_f32_e32 v189, v189
	v_exp_f32_e32 v190, v190
	v_exp_f32_e32 v191, v191
	v_exp_f32_e32 v192, v192
	v_exp_f32_e32 v193, v193
	v_exp_f32_e32 v194, v194
	v_exp_f32_e32 v195, v195
	v_mul_f32_e32 v124, v116, v124
	v_mul_f32_e32 v125, v117, v125
	v_mul_f32_e32 v126, v118, v126
	v_mul_f32_e32 v127, v119, v127
	v_mul_f32_e32 v120, v112, v120
	v_mul_f32_e32 v121, v113, v121
	v_mul_f32_e32 v122, v114, v122
	v_mul_f32_e32 v123, v115, v123
	v_add_f32_e32 v188, 1.0, v188
	v_add_f32_e32 v189, 1.0, v189
	v_add_f32_e32 v190, 1.0, v190
	v_add_f32_e32 v191, 1.0, v191
	v_add_f32_e32 v192, 1.0, v192
	v_add_f32_e32 v193, 1.0, v193
	v_add_f32_e32 v194, 1.0, v194
	v_add_f32_e32 v195, 1.0, v195
	v_rcp_f32_e32 v188, v188
	v_rcp_f32_e32 v189, v189
	v_rcp_f32_e32 v190, v190
	v_rcp_f32_e32 v191, v191
	v_rcp_f32_e32 v192, v192
	v_rcp_f32_e32 v193, v193
	v_rcp_f32_e32 v194, v194
	v_rcp_f32_e32 v195, v195
	v_mul_f32_e32 v124, v124, v158
	v_mul_f32_e32 v125, v125, v158
	v_mul_f32_e32 v126, v126, v158
	v_mul_f32_e32 v127, v127, v158
	v_mul_f32_e32 v120, v120, v158
	v_mul_f32_e32 v121, v121, v158
	v_mul_f32_e32 v122, v122, v158
	v_mul_f32_e32 v123, v123, v158
	v_mul_f32_e32 v124, v124, v188
	v_mul_f32_e32 v125, v125, v189
	v_mul_f32_e32 v126, v126, v190
	v_mul_f32_e32 v127, v127, v191
	v_mul_f32_e32 v120, v120, v192
	v_mul_f32_e32 v121, v121, v193
	v_mul_f32_e32 v122, v122, v194
	v_mul_f32_e32 v123, v123, v195
	v_cvt_pk_bf16_f32 v116, v124, v125
	v_cvt_pk_bf16_f32 v117, v126, v127
	v_cvt_pk_bf16_f32 v118, v120, v121
	v_cvt_pk_bf16_f32 v119, v122, v123
	global_store_dwordx4 v155, v[116:119], s[88:89]
	v_mul_f32_e32 v196, v104, v161
	v_mul_f32_e32 v197, v105, v161
	v_mul_f32_e32 v198, v106, v161
	v_mul_f32_e32 v199, v107, v161
	v_mul_f32_e32 v200, v100, v161
	v_mul_f32_e32 v201, v101, v161
	v_mul_f32_e32 v202, v102, v161
	v_mul_f32_e32 v203, v103, v161
	v_exp_f32_e32 v196, v196
	v_exp_f32_e32 v197, v197
	v_exp_f32_e32 v198, v198
	v_exp_f32_e32 v199, v199
	v_exp_f32_e32 v200, v200
	v_exp_f32_e32 v201, v201
	v_exp_f32_e32 v202, v202
	v_exp_f32_e32 v203, v203
	v_mul_f32_e32 v108, v104, v108
	v_mul_f32_e32 v109, v105, v109
	v_mul_f32_e32 v110, v106, v110
	v_mul_f32_e32 v111, v107, v111
	v_mul_f32_e32 v96, v100, v96
	v_mul_f32_e32 v97, v101, v97
	v_mul_f32_e32 v98, v102, v98
	v_mul_f32_e32 v99, v103, v99
	v_add_f32_e32 v196, 1.0, v196
	v_add_f32_e32 v197, 1.0, v197
	v_add_f32_e32 v198, 1.0, v198
	v_add_f32_e32 v199, 1.0, v199
	v_add_f32_e32 v200, 1.0, v200
	v_add_f32_e32 v201, 1.0, v201
	v_add_f32_e32 v202, 1.0, v202
	v_add_f32_e32 v203, 1.0, v203
	v_rcp_f32_e32 v196, v196
	v_rcp_f32_e32 v197, v197
	v_rcp_f32_e32 v198, v198
	v_rcp_f32_e32 v199, v199
	v_rcp_f32_e32 v200, v200
	v_rcp_f32_e32 v201, v201
	v_rcp_f32_e32 v202, v202
	v_rcp_f32_e32 v203, v203
	v_mul_f32_e32 v108, v108, v162
	v_mul_f32_e32 v109, v109, v162
	v_mul_f32_e32 v110, v110, v162
	v_mul_f32_e32 v111, v111, v162
	v_mul_f32_e32 v96, v96, v162
	v_mul_f32_e32 v97, v97, v162
	v_mul_f32_e32 v98, v98, v162
	v_mul_f32_e32 v99, v99, v162
	v_mul_f32_e32 v108, v108, v196
	v_mul_f32_e32 v109, v109, v197
	v_mul_f32_e32 v110, v110, v198
	v_mul_f32_e32 v111, v111, v199
	v_mul_f32_e32 v96, v96, v200
	v_mul_f32_e32 v97, v97, v201
	v_mul_f32_e32 v98, v98, v202
	v_mul_f32_e32 v99, v99, v203
	v_cvt_pk_bf16_f32 v104, v108, v109
	v_cvt_pk_bf16_f32 v105, v110, v111
	v_cvt_pk_bf16_f32 v106, v96, v97
	v_cvt_pk_bf16_f32 v107, v98, v99
	s_add_u32 s88, s88, 0x16000
	s_addc_u32 s89, s89, 0
	global_store_dwordx4 v155, v[104:107], s[88:89]
	v_mul_f32_e32 v188, v88, v165
	v_mul_f32_e32 v189, v89, v165
	v_mul_f32_e32 v190, v90, v165
	v_mul_f32_e32 v191, v91, v165
	v_mul_f32_e32 v192, v84, v165
	v_mul_f32_e32 v193, v85, v165
	v_mul_f32_e32 v194, v86, v165
	v_mul_f32_e32 v195, v87, v165
	v_exp_f32_e32 v188, v188
	v_exp_f32_e32 v189, v189
	v_exp_f32_e32 v190, v190
	v_exp_f32_e32 v191, v191
	v_exp_f32_e32 v192, v192
	v_exp_f32_e32 v193, v193
	v_exp_f32_e32 v194, v194
	v_exp_f32_e32 v195, v195
	v_mul_f32_e32 v92, v88, v92
	v_mul_f32_e32 v93, v89, v93
	v_mul_f32_e32 v94, v90, v94
	v_mul_f32_e32 v95, v91, v95
	v_mul_f32_e32 v80, v84, v80
	v_mul_f32_e32 v81, v85, v81
	v_mul_f32_e32 v82, v86, v82
	v_mul_f32_e32 v83, v87, v83
	v_add_f32_e32 v188, 1.0, v188
	v_add_f32_e32 v189, 1.0, v189
	v_add_f32_e32 v190, 1.0, v190
	v_add_f32_e32 v191, 1.0, v191
	v_add_f32_e32 v192, 1.0, v192
	v_add_f32_e32 v193, 1.0, v193
	v_add_f32_e32 v194, 1.0, v194
	v_add_f32_e32 v195, 1.0, v195
	v_rcp_f32_e32 v188, v188
	v_rcp_f32_e32 v189, v189
	v_rcp_f32_e32 v190, v190
	v_rcp_f32_e32 v191, v191
	v_rcp_f32_e32 v192, v192
	v_rcp_f32_e32 v193, v193
	v_rcp_f32_e32 v194, v194
	v_rcp_f32_e32 v195, v195
	v_mul_f32_e32 v92, v92, v166
	v_mul_f32_e32 v93, v93, v166
	v_mul_f32_e32 v94, v94, v166
	v_mul_f32_e32 v95, v95, v166
	v_mul_f32_e32 v80, v80, v166
	v_mul_f32_e32 v81, v81, v166
	v_mul_f32_e32 v82, v82, v166
	v_mul_f32_e32 v83, v83, v166
	v_mul_f32_e32 v92, v92, v188
	v_mul_f32_e32 v93, v93, v189
	v_mul_f32_e32 v94, v94, v190
	v_mul_f32_e32 v95, v95, v191
	v_mul_f32_e32 v80, v80, v192
	v_mul_f32_e32 v81, v81, v193
	v_mul_f32_e32 v82, v82, v194
	v_mul_f32_e32 v83, v83, v195
	v_cvt_pk_bf16_f32 v88, v92, v93
	v_cvt_pk_bf16_f32 v89, v94, v95
	v_cvt_pk_bf16_f32 v90, v80, v81
	v_cvt_pk_bf16_f32 v91, v82, v83
	s_add_u32 s88, s88, 0x16000
	s_addc_u32 s89, s89, 0
	global_store_dwordx4 v155, v[88:91], s[88:89]
	v_mul_f32_e32 v196, v72, v169
	v_mul_f32_e32 v197, v73, v169
	v_mul_f32_e32 v198, v74, v169
	v_mul_f32_e32 v199, v75, v169
	v_mul_f32_e32 v200, v68, v169
	v_mul_f32_e32 v201, v69, v169
	v_mul_f32_e32 v202, v70, v169
	v_mul_f32_e32 v203, v71, v169
	v_exp_f32_e32 v196, v196
	v_exp_f32_e32 v197, v197
	v_exp_f32_e32 v198, v198
	v_exp_f32_e32 v199, v199
	v_exp_f32_e32 v200, v200
	v_exp_f32_e32 v201, v201
	v_exp_f32_e32 v202, v202
	v_exp_f32_e32 v203, v203
	v_mul_f32_e32 v76, v72, v76
	v_mul_f32_e32 v77, v73, v77
	v_mul_f32_e32 v78, v74, v78
	v_mul_f32_e32 v79, v75, v79
	v_mul_f32_e32 v64, v68, v64
	v_mul_f32_e32 v65, v69, v65
	v_mul_f32_e32 v66, v70, v66
	v_mul_f32_e32 v67, v71, v67
	v_add_f32_e32 v196, 1.0, v196
	v_add_f32_e32 v197, 1.0, v197
	v_add_f32_e32 v198, 1.0, v198
	v_add_f32_e32 v199, 1.0, v199
	v_add_f32_e32 v200, 1.0, v200
	v_add_f32_e32 v201, 1.0, v201
	v_add_f32_e32 v202, 1.0, v202
	v_add_f32_e32 v203, 1.0, v203
	v_rcp_f32_e32 v196, v196
	v_rcp_f32_e32 v197, v197
	v_rcp_f32_e32 v198, v198
	v_rcp_f32_e32 v199, v199
	v_rcp_f32_e32 v200, v200
	v_rcp_f32_e32 v201, v201
	v_rcp_f32_e32 v202, v202
	v_rcp_f32_e32 v203, v203
	v_mul_f32_e32 v76, v76, v170
	v_mul_f32_e32 v77, v77, v170
	v_mul_f32_e32 v78, v78, v170
	v_mul_f32_e32 v79, v79, v170
	v_mul_f32_e32 v64, v64, v170
	v_mul_f32_e32 v65, v65, v170
	v_mul_f32_e32 v66, v66, v170
	v_mul_f32_e32 v67, v67, v170
	v_mul_f32_e32 v76, v76, v196
	v_mul_f32_e32 v77, v77, v197
	v_mul_f32_e32 v78, v78, v198
	v_mul_f32_e32 v79, v79, v199
	v_mul_f32_e32 v64, v64, v200
	v_mul_f32_e32 v65, v65, v201
	v_mul_f32_e32 v66, v66, v202
	v_mul_f32_e32 v67, v67, v203
	v_cvt_pk_bf16_f32 v72, v76, v77
	v_cvt_pk_bf16_f32 v73, v78, v79
	v_cvt_pk_bf16_f32 v74, v64, v65
	v_cvt_pk_bf16_f32 v75, v66, v67
	s_add_u32 s88, s88, 0x16000
	s_addc_u32 s89, s89, 0
	global_store_dwordx4 v155, v[72:75], s[88:89]
	v_mul_f32_e32 v188, v56, v173
	v_mul_f32_e32 v189, v57, v173
	v_mul_f32_e32 v190, v58, v173
	v_mul_f32_e32 v191, v59, v173
	v_mul_f32_e32 v192, v52, v173
	v_mul_f32_e32 v193, v53, v173
	v_mul_f32_e32 v194, v54, v173
	v_mul_f32_e32 v195, v55, v173
	v_exp_f32_e32 v188, v188
	v_exp_f32_e32 v189, v189
	v_exp_f32_e32 v190, v190
	v_exp_f32_e32 v191, v191
	v_exp_f32_e32 v192, v192
	v_exp_f32_e32 v193, v193
	v_exp_f32_e32 v194, v194
	v_exp_f32_e32 v195, v195
	v_mul_f32_e32 v60, v56, v60
	v_mul_f32_e32 v61, v57, v61
	v_mul_f32_e32 v62, v58, v62
	v_mul_f32_e32 v63, v59, v63
	v_mul_f32_e32 v48, v52, v48
	v_mul_f32_e32 v49, v53, v49
	v_mul_f32_e32 v50, v54, v50
	v_mul_f32_e32 v51, v55, v51
	v_add_f32_e32 v188, 1.0, v188
	v_add_f32_e32 v189, 1.0, v189
	v_add_f32_e32 v190, 1.0, v190
	v_add_f32_e32 v191, 1.0, v191
	v_add_f32_e32 v192, 1.0, v192
	v_add_f32_e32 v193, 1.0, v193
	v_add_f32_e32 v194, 1.0, v194
	v_add_f32_e32 v195, 1.0, v195
	v_rcp_f32_e32 v188, v188
	v_rcp_f32_e32 v189, v189
	v_rcp_f32_e32 v190, v190
	v_rcp_f32_e32 v191, v191
	v_rcp_f32_e32 v192, v192
	v_rcp_f32_e32 v193, v193
	v_rcp_f32_e32 v194, v194
	v_rcp_f32_e32 v195, v195
	v_mul_f32_e32 v60, v60, v174
	v_mul_f32_e32 v61, v61, v174
	v_mul_f32_e32 v62, v62, v174
	v_mul_f32_e32 v63, v63, v174
	v_mul_f32_e32 v48, v48, v174
	v_mul_f32_e32 v49, v49, v174
	v_mul_f32_e32 v50, v50, v174
	v_mul_f32_e32 v51, v51, v174
	v_mul_f32_e32 v60, v60, v188
	v_mul_f32_e32 v61, v61, v189
	v_mul_f32_e32 v62, v62, v190
	v_mul_f32_e32 v63, v63, v191
	v_mul_f32_e32 v48, v48, v192
	v_mul_f32_e32 v49, v49, v193
	v_mul_f32_e32 v50, v50, v194
	v_mul_f32_e32 v51, v51, v195
	v_cvt_pk_bf16_f32 v56, v60, v61
	v_cvt_pk_bf16_f32 v57, v62, v63
	v_cvt_pk_bf16_f32 v58, v48, v49
	v_cvt_pk_bf16_f32 v59, v50, v51
	s_add_u32 s88, s88, 0x6e000
	s_addc_u32 s89, s89, 0
	global_store_dwordx4 v155, v[56:59], s[88:89]
	v_mul_f32_e32 v196, v40, v177
	v_mul_f32_e32 v197, v41, v177
	v_mul_f32_e32 v198, v42, v177
	v_mul_f32_e32 v199, v43, v177
	v_mul_f32_e32 v200, v36, v177
	v_mul_f32_e32 v201, v37, v177
	v_mul_f32_e32 v202, v38, v177
	v_mul_f32_e32 v203, v39, v177
	v_exp_f32_e32 v196, v196
	v_exp_f32_e32 v197, v197
	v_exp_f32_e32 v198, v198
	v_exp_f32_e32 v199, v199
	v_exp_f32_e32 v200, v200
	v_exp_f32_e32 v201, v201
	v_exp_f32_e32 v202, v202
	v_exp_f32_e32 v203, v203
	v_mul_f32_e32 v44, v40, v44
	v_mul_f32_e32 v45, v41, v45
	v_mul_f32_e32 v46, v42, v46
	v_mul_f32_e32 v47, v43, v47
	v_mul_f32_e32 v32, v36, v32
	v_mul_f32_e32 v33, v37, v33
	v_mul_f32_e32 v34, v38, v34
	v_mul_f32_e32 v35, v39, v35
	v_add_f32_e32 v196, 1.0, v196
	v_add_f32_e32 v197, 1.0, v197
	v_add_f32_e32 v198, 1.0, v198
	v_add_f32_e32 v199, 1.0, v199
	v_add_f32_e32 v200, 1.0, v200
	v_add_f32_e32 v201, 1.0, v201
	v_add_f32_e32 v202, 1.0, v202
	v_add_f32_e32 v203, 1.0, v203
	v_rcp_f32_e32 v196, v196
	v_rcp_f32_e32 v197, v197
	v_rcp_f32_e32 v198, v198
	v_rcp_f32_e32 v199, v199
	v_rcp_f32_e32 v200, v200
	v_rcp_f32_e32 v201, v201
	v_rcp_f32_e32 v202, v202
	v_rcp_f32_e32 v203, v203
	v_mul_f32_e32 v44, v44, v178
	v_mul_f32_e32 v45, v45, v178
	v_mul_f32_e32 v46, v46, v178
	v_mul_f32_e32 v47, v47, v178
	v_mul_f32_e32 v32, v32, v178
	v_mul_f32_e32 v33, v33, v178
	v_mul_f32_e32 v34, v34, v178
	v_mul_f32_e32 v35, v35, v178
	v_mul_f32_e32 v44, v44, v196
	v_mul_f32_e32 v45, v45, v197
	v_mul_f32_e32 v46, v46, v198
	v_mul_f32_e32 v47, v47, v199
	v_mul_f32_e32 v32, v32, v200
	v_mul_f32_e32 v33, v33, v201
	v_mul_f32_e32 v34, v34, v202
	v_mul_f32_e32 v35, v35, v203
	v_cvt_pk_bf16_f32 v40, v44, v45
	v_cvt_pk_bf16_f32 v41, v46, v47
	v_cvt_pk_bf16_f32 v42, v32, v33
	v_cvt_pk_bf16_f32 v43, v34, v35
	s_add_u32 s88, s88, 0x16000
	s_addc_u32 s89, s89, 0
	global_store_dwordx4 v155, v[40:43], s[88:89]
	v_mul_f32_e32 v188, v24, v181
	v_mul_f32_e32 v189, v25, v181
	v_mul_f32_e32 v190, v26, v181
	v_mul_f32_e32 v191, v27, v181
	v_mul_f32_e32 v192, v20, v181
	v_mul_f32_e32 v193, v21, v181
	v_mul_f32_e32 v194, v22, v181
	v_mul_f32_e32 v195, v23, v181
	v_exp_f32_e32 v188, v188
	v_exp_f32_e32 v189, v189
	v_exp_f32_e32 v190, v190
	v_exp_f32_e32 v191, v191
	v_exp_f32_e32 v192, v192
	v_exp_f32_e32 v193, v193
	v_exp_f32_e32 v194, v194
	v_exp_f32_e32 v195, v195
	v_mul_f32_e32 v28, v24, v28
	v_mul_f32_e32 v29, v25, v29
	v_mul_f32_e32 v30, v26, v30
	v_mul_f32_e32 v31, v27, v31
	v_mul_f32_e32 v16, v20, v16
	v_mul_f32_e32 v17, v21, v17
	v_mul_f32_e32 v18, v22, v18
	v_mul_f32_e32 v19, v23, v19
	v_add_f32_e32 v188, 1.0, v188
	v_add_f32_e32 v189, 1.0, v189
	v_add_f32_e32 v190, 1.0, v190
	v_add_f32_e32 v191, 1.0, v191
	v_add_f32_e32 v192, 1.0, v192
	v_add_f32_e32 v193, 1.0, v193
	v_add_f32_e32 v194, 1.0, v194
	v_add_f32_e32 v195, 1.0, v195
	v_rcp_f32_e32 v188, v188
	v_rcp_f32_e32 v189, v189
	v_rcp_f32_e32 v190, v190
	v_rcp_f32_e32 v191, v191
	v_rcp_f32_e32 v192, v192
	v_rcp_f32_e32 v193, v193
	v_rcp_f32_e32 v194, v194
	v_rcp_f32_e32 v195, v195
	v_mul_f32_e32 v28, v28, v182
	v_mul_f32_e32 v29, v29, v182
	v_mul_f32_e32 v30, v30, v182
	v_mul_f32_e32 v31, v31, v182
	v_mul_f32_e32 v16, v16, v182
	v_mul_f32_e32 v17, v17, v182
	v_mul_f32_e32 v18, v18, v182
	v_mul_f32_e32 v19, v19, v182
	v_mul_f32_e32 v28, v28, v188
	v_mul_f32_e32 v29, v29, v189
	v_mul_f32_e32 v30, v30, v190
	v_mul_f32_e32 v31, v31, v191
	v_mul_f32_e32 v16, v16, v192
	v_mul_f32_e32 v17, v17, v193
	v_mul_f32_e32 v18, v18, v194
	v_mul_f32_e32 v19, v19, v195
	v_cvt_pk_bf16_f32 v24, v28, v29
	v_cvt_pk_bf16_f32 v25, v30, v31
	v_cvt_pk_bf16_f32 v26, v16, v17
	v_cvt_pk_bf16_f32 v27, v18, v19
	s_add_u32 s88, s88, 0x16000
	s_addc_u32 s89, s89, 0
	global_store_dwordx4 v155, v[24:27], s[88:89]
	v_mul_f32_e32 v196, v8, v185
	v_mul_f32_e32 v197, v9, v185
	v_mul_f32_e32 v198, v10, v185
	v_mul_f32_e32 v199, v11, v185
	v_mul_f32_e32 v200, v4, v185
	v_mul_f32_e32 v201, v5, v185
	v_mul_f32_e32 v202, v6, v185
	v_mul_f32_e32 v203, v7, v185
	v_exp_f32_e32 v196, v196
	v_exp_f32_e32 v197, v197
	v_exp_f32_e32 v198, v198
	v_exp_f32_e32 v199, v199
	v_exp_f32_e32 v200, v200
	v_exp_f32_e32 v201, v201
	v_exp_f32_e32 v202, v202
	v_exp_f32_e32 v203, v203
	v_mul_f32_e32 v12, v8, v12
	v_mul_f32_e32 v13, v9, v13
	v_mul_f32_e32 v14, v10, v14
	v_mul_f32_e32 v15, v11, v15
	v_mul_f32_e32 v0, v4, v0
	v_mul_f32_e32 v1, v5, v1
	v_mul_f32_e32 v2, v6, v2
	v_mul_f32_e32 v3, v7, v3
	v_add_f32_e32 v196, 1.0, v196
	v_add_f32_e32 v197, 1.0, v197
	v_add_f32_e32 v198, 1.0, v198
	v_add_f32_e32 v199, 1.0, v199
	v_add_f32_e32 v200, 1.0, v200
	v_add_f32_e32 v201, 1.0, v201
	v_add_f32_e32 v202, 1.0, v202
	v_add_f32_e32 v203, 1.0, v203
	v_rcp_f32_e32 v196, v196
	v_rcp_f32_e32 v197, v197
	v_rcp_f32_e32 v198, v198
	v_rcp_f32_e32 v199, v199
	v_rcp_f32_e32 v200, v200
	v_rcp_f32_e32 v201, v201
	v_rcp_f32_e32 v202, v202
	v_rcp_f32_e32 v203, v203
	v_mul_f32_e32 v12, v12, v186
	v_mul_f32_e32 v13, v13, v186
	v_mul_f32_e32 v14, v14, v186
	v_mul_f32_e32 v15, v15, v186
	v_mul_f32_e32 v0, v0, v186
	v_mul_f32_e32 v1, v1, v186
	v_mul_f32_e32 v2, v2, v186
	v_mul_f32_e32 v3, v3, v186
	v_mul_f32_e32 v12, v12, v196
	v_mul_f32_e32 v13, v13, v197
	v_mul_f32_e32 v14, v14, v198
	v_mul_f32_e32 v15, v15, v199
	v_mul_f32_e32 v0, v0, v200
	v_mul_f32_e32 v1, v1, v201
	v_mul_f32_e32 v2, v2, v202
	v_mul_f32_e32 v3, v3, v203
	v_cvt_pk_bf16_f32 v8, v12, v13
	v_cvt_pk_bf16_f32 v9, v14, v15
	v_cvt_pk_bf16_f32 v10, v0, v1
	v_cvt_pk_bf16_f32 v11, v2, v3
	s_add_u32 s88, s88, 0x16000
	s_addc_u32 s89, s89, 0
	global_store_dwordx4 v155, v[8:11], s[88:89]
	s_andn2_b64 vcc, exec, s[6:7]
	s_mov_b64 s[6:7], -1
	s_cbranch_vccnz .LBB0_180
	s_andn2_b64 vcc, exec, s[8:9]
	s_cbranch_vccnz .LBB0_179
	s_barrier
	s_branch .LBB0_179

.LBB0_419:
	v_lshrrev_b32_e32 v146, 6, v206
	v_and_b32_e32 v158, 63, v206
	v_lshrrev_b32_e32 v147, 2, v146
	v_and_b32_e32 v146, 3, v146
	v_lshlrev_b32_e32 v147, 6, v147
	v_lshrrev_b32_e32 v211, 4, v158
	v_and_b32_e32 v204, 15, v158
	v_xor_b32_e32 v205, 16, v158
	v_xor_b32_e32 v210, 32, v158
	v_lshlrev_b32_e32 v205, 2, v205
	v_lshlrev_b32_e32 v210, 2, v210
	v_add_u32_e32 v147, v147, v204
	s_lshl_b32 vcc_lo, s12, 8
	v_add_u32_e32 v147, vcc_lo, v147
	v_lshlrev_b32_e32 v158, 5, v146
	v_lshl_add_u32 v158, v211, 3, v158
	s_lshl_b32 vcc_lo, s13, 8
	v_add_u32_e32 v158, vcc_lo, v158
	v_lshlrev_b32_e32 v159, 6, v147
	v_lshl_add_u32 v159, v211, 4, v159
	v_mov_b32_e32 v204, 0x2c00
	v_mul_u32_u24_e32 v204, v147, v204
	v_lshl_add_u32 v204, v158, 1, v204
	s_add_u32 s86, s96, 0x4600000
	s_addc_u32 s87, s97, 0
	global_load_dwordx4 v[148:151], v159, s[86:87]
	global_load_dwordx4 v[160:163], v159, s[86:87] offset:1024
	global_load_dwordx4 v[164:167], v159, s[86:87] offset:2048
	global_load_dwordx4 v[168:171], v159, s[86:87] offset:3072
	s_add_u32 s86, s86, 0x2000
	s_addc_u32 s87, s87, 0
	global_load_dwordx4 v[172:175], v159, s[86:87]
	global_load_dwordx4 v[176:179], v159, s[86:87] offset:1024
	global_load_dwordx4 v[180:183], v159, s[86:87] offset:2048
	global_load_dwordx4 v[184:187], v159, s[86:87] offset:3072
	s_add_u32 s88, s96, 0x11f00000
	s_addc_u32 s89, s97, 0
	s_waitcnt vmcnt(7)
	v_add_f32_e32 v148, v148, v149
	v_add_f32_e32 v150, v150, v151
	v_add_f32_e32 v148, v148, v150
	s_waitcnt vmcnt(6)
	v_add_f32_e32 v160, v160, v161
	v_add_f32_e32 v162, v162, v163
	v_add_f32_e32 v160, v160, v162
	s_waitcnt vmcnt(5)
	v_add_f32_e32 v164, v164, v165
	v_add_f32_e32 v166, v166, v167
	v_add_f32_e32 v164, v164, v166
	s_waitcnt vmcnt(4)
	v_add_f32_e32 v168, v168, v169
	v_add_f32_e32 v170, v170, v171
	v_add_f32_e32 v168, v168, v170
	s_waitcnt vmcnt(3)
	v_add_f32_e32 v172, v172, v173
	v_add_f32_e32 v174, v174, v175
	v_add_f32_e32 v172, v172, v174
	s_waitcnt vmcnt(2)
	v_add_f32_e32 v176, v176, v177
	v_add_f32_e32 v178, v178, v179
	v_add_f32_e32 v176, v176, v178
	s_waitcnt vmcnt(1)
	v_add_f32_e32 v180, v180, v181
	v_add_f32_e32 v182, v182, v183
	v_add_f32_e32 v180, v180, v182
	s_waitcnt vmcnt(0)
	v_add_f32_e32 v184, v184, v185
	v_add_f32_e32 v186, v186, v187
	v_add_f32_e32 v184, v184, v186
	ds_bpermute_b32 v149, v205, v148
	ds_bpermute_b32 v161, v205, v160
	ds_bpermute_b32 v165, v205, v164
	ds_bpermute_b32 v169, v205, v168
	ds_bpermute_b32 v173, v205, v172
	ds_bpermute_b32 v177, v205, v176
	ds_bpermute_b32 v181, v205, v180
	ds_bpermute_b32 v185, v205, v184
	s_waitcnt lgkmcnt(0)
	v_add_f32_e32 v148, v148, v149
	v_add_f32_e32 v160, v160, v161
	v_add_f32_e32 v164, v164, v165
	v_add_f32_e32 v168, v168, v169
	v_add_f32_e32 v172, v172, v173
	v_add_f32_e32 v176, v176, v177
	v_add_f32_e32 v180, v180, v181
	v_add_f32_e32 v184, v184, v185
	s_nop 0
	ds_bpermute_b32 v149, v210, v148
	ds_bpermute_b32 v161, v210, v160
	ds_bpermute_b32 v165, v210, v164
	ds_bpermute_b32 v169, v210, v168
	ds_bpermute_b32 v173, v210, v172
	ds_bpermute_b32 v177, v210, v176
	ds_bpermute_b32 v181, v210, v180
	ds_bpermute_b32 v185, v210, v184
	s_waitcnt lgkmcnt(0)
	v_mov_b32_e32 v146, 0x358637bd
	s_mov_b32 vcc_lo, 0x3a800000
	v_add_f32_e32 v148, v148, v149
	v_add_f32_e32 v160, v160, v161
	v_add_f32_e32 v164, v164, v165
	v_add_f32_e32 v168, v168, v169
	v_add_f32_e32 v172, v172, v173
	v_add_f32_e32 v176, v176, v177
	v_add_f32_e32 v180, v180, v181
	v_add_f32_e32 v184, v184, v185
	v_fma_f32 v148, v148, vcc_lo, v146
	v_fma_f32 v160, v160, vcc_lo, v146
	v_fma_f32 v164, v164, vcc_lo, v146
	v_fma_f32 v168, v168, vcc_lo, v146
	v_fma_f32 v172, v172, vcc_lo, v146
	v_fma_f32 v176, v176, vcc_lo, v146
	v_fma_f32 v180, v180, vcc_lo, v146
	v_fma_f32 v184, v184, vcc_lo, v146
	v_rsq_f32_e32 v148, v148
	v_rsq_f32_e32 v160, v160
	v_rsq_f32_e32 v164, v164
	v_rsq_f32_e32 v168, v168
	v_rsq_f32_e32 v172, v172
	v_rsq_f32_e32 v176, v176
	v_rsq_f32_e32 v180, v180
	v_rsq_f32_e32 v184, v184
	s_nop 0
	v_mul_f32_e32 v124, v124, v148
	v_mul_f32_e32 v125, v125, v148
	v_mul_f32_e32 v126, v126, v148
	v_mul_f32_e32 v127, v127, v148
	v_mul_f32_e32 v120, v120, v148
	v_mul_f32_e32 v121, v121, v148
	v_mul_f32_e32 v122, v122, v148
	v_mul_f32_e32 v123, v123, v148
	v_cvt_pk_bf16_f32 v124, v124, v125
	v_cvt_pk_bf16_f32 v125, v126, v127
	v_cvt_pk_bf16_f32 v126, v120, v121
	v_cvt_pk_bf16_f32 v127, v122, v123
	global_store_dwordx4 v204, v[124:127], s[88:89]
	v_mul_f32_e32 v116, v116, v148
	v_mul_f32_e32 v117, v117, v148
	v_mul_f32_e32 v118, v118, v148
	v_mul_f32_e32 v119, v119, v148
	v_mul_f32_e32 v112, v112, v148
	v_mul_f32_e32 v113, v113, v148
	v_mul_f32_e32 v114, v114, v148
	v_mul_f32_e32 v115, v115, v148
	v_cvt_pk_bf16_f32 v116, v116, v117
	v_cvt_pk_bf16_f32 v117, v118, v119
	v_cvt_pk_bf16_f32 v118, v112, v113
	v_cvt_pk_bf16_f32 v119, v114, v115
	global_store_dwordx4 v204, v[116:119], s[88:89] offset:256
	s_add_u32 s88, s88, 0x2c000
	s_addc_u32 s89, s89, 0
	v_mul_f32_e32 v108, v108, v160
	v_mul_f32_e32 v109, v109, v160
	v_mul_f32_e32 v110, v110, v160
	v_mul_f32_e32 v111, v111, v160
	v_mul_f32_e32 v104, v104, v160
	v_mul_f32_e32 v105, v105, v160
	v_mul_f32_e32 v106, v106, v160
	v_mul_f32_e32 v107, v107, v160
	v_cvt_pk_bf16_f32 v108, v108, v109
	v_cvt_pk_bf16_f32 v109, v110, v111
	v_cvt_pk_bf16_f32 v110, v104, v105
	v_cvt_pk_bf16_f32 v111, v106, v107
	global_store_dwordx4 v204, v[108:111], s[88:89]
	v_mul_f32_e32 v100, v100, v160
	v_mul_f32_e32 v101, v101, v160
	v_mul_f32_e32 v102, v102, v160
	v_mul_f32_e32 v103, v103, v160
	v_mul_f32_e32 v96, v96, v160
	v_mul_f32_e32 v97, v97, v160
	v_mul_f32_e32 v98, v98, v160
	v_mul_f32_e32 v99, v99, v160
	v_cvt_pk_bf16_f32 v100, v100, v101
	v_cvt_pk_bf16_f32 v101, v102, v103
	v_cvt_pk_bf16_f32 v102, v96, v97
	v_cvt_pk_bf16_f32 v103, v98, v99
	global_store_dwordx4 v204, v[100:103], s[88:89] offset:256
	s_add_u32 s88, s88, 0x2c000
	s_addc_u32 s89, s89, 0
	v_mul_f32_e32 v92, v92, v164
	v_mul_f32_e32 v93, v93, v164
	v_mul_f32_e32 v94, v94, v164
	v_mul_f32_e32 v95, v95, v164
	v_mul_f32_e32 v88, v88, v164
	v_mul_f32_e32 v89, v89, v164
	v_mul_f32_e32 v90, v90, v164
	v_mul_f32_e32 v91, v91, v164
	v_cvt_pk_bf16_f32 v92, v92, v93
	v_cvt_pk_bf16_f32 v93, v94, v95
	v_cvt_pk_bf16_f32 v94, v88, v89
	v_cvt_pk_bf16_f32 v95, v90, v91
	global_store_dwordx4 v204, v[92:95], s[88:89]
	v_mul_f32_e32 v84, v84, v164
	v_mul_f32_e32 v85, v85, v164
	v_mul_f32_e32 v86, v86, v164
	v_mul_f32_e32 v87, v87, v164
	v_mul_f32_e32 v80, v80, v164
	v_mul_f32_e32 v81, v81, v164
	v_mul_f32_e32 v82, v82, v164
	v_mul_f32_e32 v83, v83, v164
	v_cvt_pk_bf16_f32 v84, v84, v85
	v_cvt_pk_bf16_f32 v85, v86, v87
	v_cvt_pk_bf16_f32 v86, v80, v81
	v_cvt_pk_bf16_f32 v87, v82, v83
	global_store_dwordx4 v204, v[84:87], s[88:89] offset:256
	s_add_u32 s88, s88, 0x2c000
	s_addc_u32 s89, s89, 0
	v_mul_f32_e32 v76, v76, v168
	v_mul_f32_e32 v77, v77, v168
	v_mul_f32_e32 v78, v78, v168
	v_mul_f32_e32 v79, v79, v168
	v_mul_f32_e32 v72, v72, v168
	v_mul_f32_e32 v73, v73, v168
	v_mul_f32_e32 v74, v74, v168
	v_mul_f32_e32 v75, v75, v168
	v_cvt_pk_bf16_f32 v76, v76, v77
	v_cvt_pk_bf16_f32 v77, v78, v79
	v_cvt_pk_bf16_f32 v78, v72, v73
	v_cvt_pk_bf16_f32 v79, v74, v75
	global_store_dwordx4 v204, v[76:79], s[88:89]
	v_mul_f32_e32 v68, v68, v168
	v_mul_f32_e32 v69, v69, v168
	v_mul_f32_e32 v70, v70, v168
	v_mul_f32_e32 v71, v71, v168
	v_mul_f32_e32 v64, v64, v168
	v_mul_f32_e32 v65, v65, v168
	v_mul_f32_e32 v66, v66, v168
	v_mul_f32_e32 v67, v67, v168
	v_cvt_pk_bf16_f32 v68, v68, v69
	v_cvt_pk_bf16_f32 v69, v70, v71
	v_cvt_pk_bf16_f32 v70, v64, v65
	v_cvt_pk_bf16_f32 v71, v66, v67
	global_store_dwordx4 v204, v[68:71], s[88:89] offset:256
	s_add_u32 s88, s88, 0xdc000
	s_addc_u32 s89, s89, 0
	v_mul_f32_e32 v60, v60, v172
	v_mul_f32_e32 v61, v61, v172
	v_mul_f32_e32 v62, v62, v172
	v_mul_f32_e32 v63, v63, v172
	v_mul_f32_e32 v56, v56, v172
	v_mul_f32_e32 v57, v57, v172
	v_mul_f32_e32 v58, v58, v172
	v_mul_f32_e32 v59, v59, v172
	v_cvt_pk_bf16_f32 v60, v60, v61
	v_cvt_pk_bf16_f32 v61, v62, v63
	v_cvt_pk_bf16_f32 v62, v56, v57
	v_cvt_pk_bf16_f32 v63, v58, v59
	global_store_dwordx4 v204, v[60:63], s[88:89]
	v_mul_f32_e32 v52, v52, v172
	v_mul_f32_e32 v53, v53, v172
	v_mul_f32_e32 v54, v54, v172
	v_mul_f32_e32 v55, v55, v172
	v_mul_f32_e32 v48, v48, v172
	v_mul_f32_e32 v49, v49, v172
	v_mul_f32_e32 v50, v50, v172
	v_mul_f32_e32 v51, v51, v172
	v_cvt_pk_bf16_f32 v52, v52, v53
	v_cvt_pk_bf16_f32 v53, v54, v55
	v_cvt_pk_bf16_f32 v54, v48, v49
	v_cvt_pk_bf16_f32 v55, v50, v51
	global_store_dwordx4 v204, v[52:55], s[88:89] offset:256
	s_add_u32 s88, s88, 0x2c000
	s_addc_u32 s89, s89, 0
	v_mul_f32_e32 v44, v44, v176
	v_mul_f32_e32 v45, v45, v176
	v_mul_f32_e32 v46, v46, v176
	v_mul_f32_e32 v47, v47, v176
	v_mul_f32_e32 v40, v40, v176
	v_mul_f32_e32 v41, v41, v176
	v_mul_f32_e32 v42, v42, v176
	v_mul_f32_e32 v43, v43, v176
	v_cvt_pk_bf16_f32 v44, v44, v45
	v_cvt_pk_bf16_f32 v45, v46, v47
	v_cvt_pk_bf16_f32 v46, v40, v41
	v_cvt_pk_bf16_f32 v47, v42, v43
	global_store_dwordx4 v204, v[44:47], s[88:89]
	v_mul_f32_e32 v36, v36, v176
	v_mul_f32_e32 v37, v37, v176
	v_mul_f32_e32 v38, v38, v176
	v_mul_f32_e32 v39, v39, v176
	v_mul_f32_e32 v32, v32, v176
	v_mul_f32_e32 v33, v33, v176
	v_mul_f32_e32 v34, v34, v176
	v_mul_f32_e32 v35, v35, v176
	v_cvt_pk_bf16_f32 v36, v36, v37
	v_cvt_pk_bf16_f32 v37, v38, v39
	v_cvt_pk_bf16_f32 v38, v32, v33
	v_cvt_pk_bf16_f32 v39, v34, v35
	global_store_dwordx4 v204, v[36:39], s[88:89] offset:256
	s_add_u32 s88, s88, 0x2c000
	s_addc_u32 s89, s89, 0
	v_mul_f32_e32 v28, v28, v180
	v_mul_f32_e32 v29, v29, v180
	v_mul_f32_e32 v30, v30, v180
	v_mul_f32_e32 v31, v31, v180
	v_mul_f32_e32 v24, v24, v180
	v_mul_f32_e32 v25, v25, v180
	v_mul_f32_e32 v26, v26, v180
	v_mul_f32_e32 v27, v27, v180
	v_cvt_pk_bf16_f32 v28, v28, v29
	v_cvt_pk_bf16_f32 v29, v30, v31
	v_cvt_pk_bf16_f32 v30, v24, v25
	v_cvt_pk_bf16_f32 v31, v26, v27
	global_store_dwordx4 v204, v[28:31], s[88:89]
	v_mul_f32_e32 v20, v20, v180
	v_mul_f32_e32 v21, v21, v180
	v_mul_f32_e32 v22, v22, v180
	v_mul_f32_e32 v23, v23, v180
	v_mul_f32_e32 v16, v16, v180
	v_mul_f32_e32 v17, v17, v180
	v_mul_f32_e32 v18, v18, v180
	v_mul_f32_e32 v19, v19, v180
	v_cvt_pk_bf16_f32 v20, v20, v21
	v_cvt_pk_bf16_f32 v21, v22, v23
	v_cvt_pk_bf16_f32 v22, v16, v17
	v_cvt_pk_bf16_f32 v23, v18, v19
	global_store_dwordx4 v204, v[20:23], s[88:89] offset:256
	s_add_u32 s88, s88, 0x2c000
	s_addc_u32 s89, s89, 0
	v_mul_f32_e32 v12, v12, v184
	v_mul_f32_e32 v13, v13, v184
	v_mul_f32_e32 v14, v14, v184
	v_mul_f32_e32 v15, v15, v184
	v_mul_f32_e32 v8, v8, v184
	v_mul_f32_e32 v9, v9, v184
	v_mul_f32_e32 v10, v10, v184
	v_mul_f32_e32 v11, v11, v184
	v_cvt_pk_bf16_f32 v12, v12, v13
	v_cvt_pk_bf16_f32 v13, v14, v15
	v_cvt_pk_bf16_f32 v14, v8, v9
	v_cvt_pk_bf16_f32 v15, v10, v11
	global_store_dwordx4 v204, v[12:15], s[88:89]
	v_mul_f32_e32 v4, v4, v184
	v_mul_f32_e32 v5, v5, v184
	v_mul_f32_e32 v6, v6, v184
	v_mul_f32_e32 v7, v7, v184
	v_mul_f32_e32 v0, v0, v184
	v_mul_f32_e32 v1, v1, v184
	v_mul_f32_e32 v2, v2, v184
	v_mul_f32_e32 v3, v3, v184
	v_cvt_pk_bf16_f32 v4, v4, v5
	v_cvt_pk_bf16_f32 v5, v6, v7
	v_cvt_pk_bf16_f32 v6, v0, v1
	v_cvt_pk_bf16_f32 v7, v2, v3
	global_store_dwordx4 v204, v[4:7], s[88:89] offset:256
	s_andn2_b64 vcc, exec, s[10:11]
	s_mov_b64 s[10:11], -1
	s_cbranch_vccnz .LBB0_408
	s_andn2_b64 vcc, exec, s[14:15]
	s_cbranch_vccnz .LBB0_407
	s_barrier
	s_branch .LBB0_407

.LBB0_1134:
	v_lshrrev_b32_e32 v155, 6, v206
	v_and_b32_e32 v211, 63, v206
	v_lshrrev_b32_e32 v210, 2, v155
	v_and_b32_e32 v155, 3, v155
	v_lshlrev_b32_e32 v210, 6, v210
	v_lshrrev_b32_e32 v218, 4, v211
	v_and_b32_e32 v221, 15, v211
	v_xor_b32_e32 v216, 16, v211
	v_xor_b32_e32 v217, 32, v211
	v_lshlrev_b32_e32 v216, 2, v216
	v_lshlrev_b32_e32 v217, 2, v217
	v_add_u32_e32 v210, v210, v221
	s_lshl_b32 vcc_lo, s40, 8
	v_add_u32_e32 v210, vcc_lo, v210
	v_lshlrev_b32_e32 v211, 5, v155
	v_lshl_add_u32 v211, v218, 3, v211
	s_lshl_b32 vcc_lo, s65, 8
	v_add_u32_e32 v211, vcc_lo, v211
	v_lshlrev_b32_e32 v220, 6, v210
	v_lshl_add_u32 v220, v218, 4, v220
	v_mov_b32_e32 v221, 0x800
	v_mul_u32_u24_e32 v221, v210, v221
	v_lshl_add_u32 v221, v211, 1, v221
	s_add_u32 s86, s96, 0x4b00000
	s_addc_u32 s87, s97, 0
	global_load_dwordx4 v[144:147], v220, s[86:87]
	global_load_dwordx4 v[156:159], v220, s[86:87] offset:1024
	global_load_dwordx4 v[160:163], v220, s[86:87] offset:2048
	global_load_dwordx4 v[164:167], v220, s[86:87] offset:3072
	s_add_u32 s86, s86, 0x2000
	s_addc_u32 s87, s87, 0
	global_load_dwordx4 v[168:171], v220, s[86:87]
	global_load_dwordx4 v[172:175], v220, s[86:87] offset:1024
	global_load_dwordx4 v[176:179], v220, s[86:87] offset:2048
	global_load_dwordx4 v[180:183], v220, s[86:87] offset:3072
	s_add_u32 s88, s96, 0x11f00000
	s_addc_u32 s89, s97, 0
	s_waitcnt vmcnt(7)
	v_add_f32_e32 v144, v144, v145
	v_add_f32_e32 v146, v146, v147
	v_add_f32_e32 v144, v144, v146
	s_waitcnt vmcnt(6)
	v_add_f32_e32 v156, v156, v157
	v_add_f32_e32 v158, v158, v159
	v_add_f32_e32 v156, v156, v158
	s_waitcnt vmcnt(5)
	v_add_f32_e32 v160, v160, v161
	v_add_f32_e32 v162, v162, v163
	v_add_f32_e32 v160, v160, v162
	s_waitcnt vmcnt(4)
	v_add_f32_e32 v164, v164, v165
	v_add_f32_e32 v166, v166, v167
	v_add_f32_e32 v164, v164, v166
	s_waitcnt vmcnt(3)
	v_add_f32_e32 v168, v168, v169
	v_add_f32_e32 v170, v170, v171
	v_add_f32_e32 v168, v168, v170
	s_waitcnt vmcnt(2)
	v_add_f32_e32 v172, v172, v173
	v_add_f32_e32 v174, v174, v175
	v_add_f32_e32 v172, v172, v174
	s_waitcnt vmcnt(1)
	v_add_f32_e32 v176, v176, v177
	v_add_f32_e32 v178, v178, v179
	v_add_f32_e32 v176, v176, v178
	s_waitcnt vmcnt(0)
	v_add_f32_e32 v180, v180, v181
	v_add_f32_e32 v182, v182, v183
	v_add_f32_e32 v180, v180, v182
	ds_bpermute_b32 v145, v216, v144
	ds_bpermute_b32 v157, v216, v156
	ds_bpermute_b32 v161, v216, v160
	ds_bpermute_b32 v165, v216, v164
	ds_bpermute_b32 v169, v216, v168
	ds_bpermute_b32 v173, v216, v172
	ds_bpermute_b32 v177, v216, v176
	ds_bpermute_b32 v181, v216, v180
	s_waitcnt lgkmcnt(0)
	v_add_f32_e32 v144, v144, v145
	v_add_f32_e32 v156, v156, v157
	v_add_f32_e32 v160, v160, v161
	v_add_f32_e32 v164, v164, v165
	v_add_f32_e32 v168, v168, v169
	v_add_f32_e32 v172, v172, v173
	v_add_f32_e32 v176, v176, v177
	v_add_f32_e32 v180, v180, v181
	s_nop 0
	ds_bpermute_b32 v145, v217, v144
	ds_bpermute_b32 v157, v217, v156
	ds_bpermute_b32 v161, v217, v160
	ds_bpermute_b32 v165, v217, v164
	ds_bpermute_b32 v169, v217, v168
	ds_bpermute_b32 v173, v217, v172
	ds_bpermute_b32 v177, v217, v176
	ds_bpermute_b32 v181, v217, v180
	s_waitcnt lgkmcnt(0)
	v_mov_b32_e32 v155, 0x358637bd
	s_mov_b32 vcc_lo, 0x3a800000
	v_add_f32_e32 v144, v144, v145
	v_add_f32_e32 v156, v156, v157
	v_add_f32_e32 v160, v160, v161
	v_add_f32_e32 v164, v164, v165
	v_add_f32_e32 v168, v168, v169
	v_add_f32_e32 v172, v172, v173
	v_add_f32_e32 v176, v176, v177
	v_add_f32_e32 v180, v180, v181
	v_fma_f32 v144, v144, vcc_lo, v155
	v_fma_f32 v156, v156, vcc_lo, v155
	v_fma_f32 v160, v160, vcc_lo, v155
	v_fma_f32 v164, v164, vcc_lo, v155
	v_fma_f32 v168, v168, vcc_lo, v155
	v_fma_f32 v172, v172, vcc_lo, v155
	v_fma_f32 v176, v176, vcc_lo, v155
	v_fma_f32 v180, v180, vcc_lo, v155
	v_rsq_f32_e32 v144, v144
	v_rsq_f32_e32 v156, v156
	v_rsq_f32_e32 v160, v160
	v_rsq_f32_e32 v164, v164
	v_rsq_f32_e32 v168, v168
	v_rsq_f32_e32 v172, v172
	v_rsq_f32_e32 v176, v176
	v_rsq_f32_e32 v180, v180
	s_nop 0
	v_mul_f32_e32 v144, 0x3db8aa3b, v144
	v_mul_f32_e32 v156, 0x3db8aa3b, v156
	v_mul_f32_e32 v160, 0x3db8aa3b, v160
	v_mul_f32_e32 v164, 0x3db8aa3b, v164
	v_mul_f32_e32 v168, 0x3db8aa3b, v168
	v_mul_f32_e32 v172, 0x3db8aa3b, v172
	v_mul_f32_e32 v176, 0x3db8aa3b, v176
	v_mul_f32_e32 v180, 0x3db8aa3b, v180
	v_mul_f32_e32 v124, v124, v144
	v_mul_f32_e32 v125, v125, v144
	v_mul_f32_e32 v126, v126, v144
	v_mul_f32_e32 v127, v127, v144
	v_mul_f32_e32 v120, v120, v144
	v_mul_f32_e32 v121, v121, v144
	v_mul_f32_e32 v122, v122, v144
	v_mul_f32_e32 v123, v123, v144
	v_cvt_pk_bf16_f32 v124, v124, v125
	v_cvt_pk_bf16_f32 v125, v126, v127
	v_cvt_pk_bf16_f32 v126, v120, v121
	v_cvt_pk_bf16_f32 v127, v122, v123
	global_store_dwordx4 v221, v[124:127], s[88:89]
	v_mul_f32_e32 v116, v116, v144
	v_mul_f32_e32 v117, v117, v144
	v_mul_f32_e32 v118, v118, v144
	v_mul_f32_e32 v119, v119, v144
	v_mul_f32_e32 v112, v112, v144
	v_mul_f32_e32 v113, v113, v144
	v_mul_f32_e32 v114, v114, v144
	v_mul_f32_e32 v115, v115, v144
	v_cvt_pk_bf16_f32 v116, v116, v117
	v_cvt_pk_bf16_f32 v117, v118, v119
	v_cvt_pk_bf16_f32 v118, v112, v113
	v_cvt_pk_bf16_f32 v119, v114, v115
	global_store_dwordx4 v221, v[116:119], s[88:89] offset:256
	s_add_u32 s88, s88, 0x8000
	s_addc_u32 s89, s89, 0
	v_mul_f32_e32 v108, v108, v156
	v_mul_f32_e32 v109, v109, v156
	v_mul_f32_e32 v110, v110, v156
	v_mul_f32_e32 v111, v111, v156
	v_mul_f32_e32 v104, v104, v156
	v_mul_f32_e32 v105, v105, v156
	v_mul_f32_e32 v106, v106, v156
	v_mul_f32_e32 v107, v107, v156
	v_cvt_pk_bf16_f32 v108, v108, v109
	v_cvt_pk_bf16_f32 v109, v110, v111
	v_cvt_pk_bf16_f32 v110, v104, v105
	v_cvt_pk_bf16_f32 v111, v106, v107
	global_store_dwordx4 v221, v[108:111], s[88:89]
	v_mul_f32_e32 v100, v100, v156
	v_mul_f32_e32 v101, v101, v156
	v_mul_f32_e32 v102, v102, v156
	v_mul_f32_e32 v103, v103, v156
	v_mul_f32_e32 v96, v96, v156
	v_mul_f32_e32 v97, v97, v156
	v_mul_f32_e32 v98, v98, v156
	v_mul_f32_e32 v99, v99, v156
	v_cvt_pk_bf16_f32 v100, v100, v101
	v_cvt_pk_bf16_f32 v101, v102, v103
	v_cvt_pk_bf16_f32 v102, v96, v97
	v_cvt_pk_bf16_f32 v103, v98, v99
	global_store_dwordx4 v221, v[100:103], s[88:89] offset:256
	s_add_u32 s88, s88, 0x8000
	s_addc_u32 s89, s89, 0
	v_mul_f32_e32 v92, v92, v160
	v_mul_f32_e32 v93, v93, v160
	v_mul_f32_e32 v94, v94, v160
	v_mul_f32_e32 v95, v95, v160
	v_mul_f32_e32 v88, v88, v160
	v_mul_f32_e32 v89, v89, v160
	v_mul_f32_e32 v90, v90, v160
	v_mul_f32_e32 v91, v91, v160
	v_cvt_pk_bf16_f32 v92, v92, v93
	v_cvt_pk_bf16_f32 v93, v94, v95
	v_cvt_pk_bf16_f32 v94, v88, v89
	v_cvt_pk_bf16_f32 v95, v90, v91
	global_store_dwordx4 v221, v[92:95], s[88:89]
	v_mul_f32_e32 v84, v84, v160
	v_mul_f32_e32 v85, v85, v160
	v_mul_f32_e32 v86, v86, v160
	v_mul_f32_e32 v87, v87, v160
	v_mul_f32_e32 v80, v80, v160
	v_mul_f32_e32 v81, v81, v160
	v_mul_f32_e32 v82, v82, v160
	v_mul_f32_e32 v83, v83, v160
	v_cvt_pk_bf16_f32 v84, v84, v85
	v_cvt_pk_bf16_f32 v85, v86, v87
	v_cvt_pk_bf16_f32 v86, v80, v81
	v_cvt_pk_bf16_f32 v87, v82, v83
	global_store_dwordx4 v221, v[84:87], s[88:89] offset:256
	s_add_u32 s88, s88, 0x8000
	s_addc_u32 s89, s89, 0
	v_mul_f32_e32 v76, v76, v164
	v_mul_f32_e32 v77, v77, v164
	v_mul_f32_e32 v78, v78, v164
	v_mul_f32_e32 v79, v79, v164
	v_mul_f32_e32 v72, v72, v164
	v_mul_f32_e32 v73, v73, v164
	v_mul_f32_e32 v74, v74, v164
	v_mul_f32_e32 v75, v75, v164
	v_cvt_pk_bf16_f32 v76, v76, v77
	v_cvt_pk_bf16_f32 v77, v78, v79
	v_cvt_pk_bf16_f32 v78, v72, v73
	v_cvt_pk_bf16_f32 v79, v74, v75
	global_store_dwordx4 v221, v[76:79], s[88:89]
	v_mul_f32_e32 v68, v68, v164
	v_mul_f32_e32 v69, v69, v164
	v_mul_f32_e32 v70, v70, v164
	v_mul_f32_e32 v71, v71, v164
	v_mul_f32_e32 v64, v64, v164
	v_mul_f32_e32 v65, v65, v164
	v_mul_f32_e32 v66, v66, v164
	v_mul_f32_e32 v67, v67, v164
	v_cvt_pk_bf16_f32 v68, v68, v69
	v_cvt_pk_bf16_f32 v69, v70, v71
	v_cvt_pk_bf16_f32 v70, v64, v65
	v_cvt_pk_bf16_f32 v71, v66, v67
	global_store_dwordx4 v221, v[68:71], s[88:89] offset:256
	s_add_u32 s88, s88, 0x28000
	s_addc_u32 s89, s89, 0
	v_mul_f32_e32 v60, v60, v168
	v_mul_f32_e32 v61, v61, v168
	v_mul_f32_e32 v62, v62, v168
	v_mul_f32_e32 v63, v63, v168
	v_mul_f32_e32 v56, v56, v168
	v_mul_f32_e32 v57, v57, v168
	v_mul_f32_e32 v58, v58, v168
	v_mul_f32_e32 v59, v59, v168
	v_cvt_pk_bf16_f32 v60, v60, v61
	v_cvt_pk_bf16_f32 v61, v62, v63
	v_cvt_pk_bf16_f32 v62, v56, v57
	v_cvt_pk_bf16_f32 v63, v58, v59
	global_store_dwordx4 v221, v[60:63], s[88:89]
	v_mul_f32_e32 v52, v52, v168
	v_mul_f32_e32 v53, v53, v168
	v_mul_f32_e32 v54, v54, v168
	v_mul_f32_e32 v55, v55, v168
	v_mul_f32_e32 v48, v48, v168
	v_mul_f32_e32 v49, v49, v168
	v_mul_f32_e32 v50, v50, v168
	v_mul_f32_e32 v51, v51, v168
	v_cvt_pk_bf16_f32 v52, v52, v53
	v_cvt_pk_bf16_f32 v53, v54, v55
	v_cvt_pk_bf16_f32 v54, v48, v49
	v_cvt_pk_bf16_f32 v55, v50, v51
	global_store_dwordx4 v221, v[52:55], s[88:89] offset:256
	s_add_u32 s88, s88, 0x8000
	s_addc_u32 s89, s89, 0
	v_mul_f32_e32 v44, v44, v172
	v_mul_f32_e32 v45, v45, v172
	v_mul_f32_e32 v46, v46, v172
	v_mul_f32_e32 v47, v47, v172
	v_mul_f32_e32 v40, v40, v172
	v_mul_f32_e32 v41, v41, v172
	v_mul_f32_e32 v42, v42, v172
	v_mul_f32_e32 v43, v43, v172
	v_cvt_pk_bf16_f32 v44, v44, v45
	v_cvt_pk_bf16_f32 v45, v46, v47
	v_cvt_pk_bf16_f32 v46, v40, v41
	v_cvt_pk_bf16_f32 v47, v42, v43
	global_store_dwordx4 v221, v[44:47], s[88:89]
	v_mul_f32_e32 v36, v36, v172
	v_mul_f32_e32 v37, v37, v172
	v_mul_f32_e32 v38, v38, v172
	v_mul_f32_e32 v39, v39, v172
	v_mul_f32_e32 v32, v32, v172
	v_mul_f32_e32 v33, v33, v172
	v_mul_f32_e32 v34, v34, v172
	v_mul_f32_e32 v35, v35, v172
	v_cvt_pk_bf16_f32 v36, v36, v37
	v_cvt_pk_bf16_f32 v37, v38, v39
	v_cvt_pk_bf16_f32 v38, v32, v33
	v_cvt_pk_bf16_f32 v39, v34, v35
	global_store_dwordx4 v221, v[36:39], s[88:89] offset:256
	s_add_u32 s88, s88, 0x8000
	s_addc_u32 s89, s89, 0
	v_mul_f32_e32 v28, v28, v176
	v_mul_f32_e32 v29, v29, v176
	v_mul_f32_e32 v30, v30, v176
	v_mul_f32_e32 v31, v31, v176
	v_mul_f32_e32 v24, v24, v176
	v_mul_f32_e32 v25, v25, v176
	v_mul_f32_e32 v26, v26, v176
	v_mul_f32_e32 v27, v27, v176
	v_cvt_pk_bf16_f32 v28, v28, v29
	v_cvt_pk_bf16_f32 v29, v30, v31
	v_cvt_pk_bf16_f32 v30, v24, v25
	v_cvt_pk_bf16_f32 v31, v26, v27
	global_store_dwordx4 v221, v[28:31], s[88:89]
	v_mul_f32_e32 v20, v20, v176
	v_mul_f32_e32 v21, v21, v176
	v_mul_f32_e32 v22, v22, v176
	v_mul_f32_e32 v23, v23, v176
	v_mul_f32_e32 v16, v16, v176
	v_mul_f32_e32 v17, v17, v176
	v_mul_f32_e32 v18, v18, v176
	v_mul_f32_e32 v19, v19, v176
	v_cvt_pk_bf16_f32 v20, v20, v21
	v_cvt_pk_bf16_f32 v21, v22, v23
	v_cvt_pk_bf16_f32 v22, v16, v17
	v_cvt_pk_bf16_f32 v23, v18, v19
	global_store_dwordx4 v221, v[20:23], s[88:89] offset:256
	s_add_u32 s88, s88, 0x8000
	s_addc_u32 s89, s89, 0
	v_mul_f32_e32 v12, v12, v180
	v_mul_f32_e32 v13, v13, v180
	v_mul_f32_e32 v14, v14, v180
	v_mul_f32_e32 v15, v15, v180
	v_mul_f32_e32 v8, v8, v180
	v_mul_f32_e32 v9, v9, v180
	v_mul_f32_e32 v10, v10, v180
	v_mul_f32_e32 v11, v11, v180
	v_cvt_pk_bf16_f32 v12, v12, v13
	v_cvt_pk_bf16_f32 v13, v14, v15
	v_cvt_pk_bf16_f32 v14, v8, v9
	v_cvt_pk_bf16_f32 v15, v10, v11
	global_store_dwordx4 v221, v[12:15], s[88:89]
	v_mul_f32_e32 v4, v4, v180
	v_mul_f32_e32 v5, v5, v180
	v_mul_f32_e32 v6, v6, v180
	v_mul_f32_e32 v7, v7, v180
	v_mul_f32_e32 v0, v0, v180
	v_mul_f32_e32 v1, v1, v180
	v_mul_f32_e32 v2, v2, v180
	v_mul_f32_e32 v3, v3, v180
	v_cvt_pk_bf16_f32 v4, v4, v5
	v_cvt_pk_bf16_f32 v5, v6, v7
	v_cvt_pk_bf16_f32 v6, v0, v1
	v_cvt_pk_bf16_f32 v7, v2, v3
	global_store_dwordx4 v221, v[4:7], s[88:89] offset:256
	s_andn2_b64 vcc, exec, s[10:11]
	s_mov_b64 s[10:11], -1
	s_cbranch_vccnz .LBB0_1123
	s_andn2_b64 vcc, exec, s[12:13]
	s_cbranch_vccnz .LBB0_1122
	s_barrier
	s_branch .LBB0_1122

.LBB0_1410:
	v_lshrrev_b32_e32 v144, 6, v206
	v_and_b32_e32 v153, 63, v206
	v_lshrrev_b32_e32 v145, 2, v144
	v_and_b32_e32 v144, 3, v144
	v_lshlrev_b32_e32 v145, 6, v145
	v_lshrrev_b32_e32 v210, 4, v153
	v_and_b32_e32 v155, 15, v153
	v_xor_b32_e32 v204, 16, v153
	v_xor_b32_e32 v205, 32, v153
	v_lshlrev_b32_e32 v204, 2, v204
	v_lshlrev_b32_e32 v205, 2, v205
	v_add_u32_e32 v145, v145, v155
	s_lshl_b32 vcc_lo, s30, 8
	v_add_u32_e32 v145, vcc_lo, v145
	v_lshlrev_b32_e32 v153, 5, v144
	v_lshl_add_u32 v153, v210, 3, v153
	s_lshl_b32 vcc_lo, s64, 7
	v_add_u32_e32 v153, vcc_lo, v153
	v_lshlrev_b32_e32 v154, 6, v145
	v_lshl_add_u32 v154, v210, 4, v154
	v_mov_b32_e32 v155, 0x1600
	v_mul_u32_u24_e32 v155, v145, v155
	v_lshl_add_u32 v155, v153, 1, v155
	s_add_u32 s86, s96, 0x5000000
	s_addc_u32 s87, s97, 0
	global_load_dwordx4 v[156:159], v154, s[86:87]
	global_load_dwordx4 v[160:163], v154, s[86:87] offset:1024
	global_load_dwordx4 v[164:167], v154, s[86:87] offset:2048
	global_load_dwordx4 v[168:171], v154, s[86:87] offset:3072
	s_add_u32 s86, s86, 0x2000
	s_addc_u32 s87, s87, 0
	global_load_dwordx4 v[172:175], v154, s[86:87]
	global_load_dwordx4 v[176:179], v154, s[86:87] offset:1024
	global_load_dwordx4 v[180:183], v154, s[86:87] offset:2048
	global_load_dwordx4 v[184:187], v154, s[86:87] offset:3072
	s_add_u32 s88, s96, 0x11f00000
	s_addc_u32 s89, s97, 0
	s_waitcnt vmcnt(7)
	v_add_f32_e32 v156, v156, v157
	v_add_f32_e32 v158, v158, v159
	v_add_f32_e32 v156, v156, v158
	s_waitcnt vmcnt(6)
	v_add_f32_e32 v160, v160, v161
	v_add_f32_e32 v162, v162, v163
	v_add_f32_e32 v160, v160, v162
	s_waitcnt vmcnt(5)
	v_add_f32_e32 v164, v164, v165
	v_add_f32_e32 v166, v166, v167
	v_add_f32_e32 v164, v164, v166
	s_waitcnt vmcnt(4)
	v_add_f32_e32 v168, v168, v169
	v_add_f32_e32 v170, v170, v171
	v_add_f32_e32 v168, v168, v170
	s_waitcnt vmcnt(3)
	v_add_f32_e32 v172, v172, v173
	v_add_f32_e32 v174, v174, v175
	v_add_f32_e32 v172, v172, v174
	s_waitcnt vmcnt(2)
	v_add_f32_e32 v176, v176, v177
	v_add_f32_e32 v178, v178, v179
	v_add_f32_e32 v176, v176, v178
	s_waitcnt vmcnt(1)
	v_add_f32_e32 v180, v180, v181
	v_add_f32_e32 v182, v182, v183
	v_add_f32_e32 v180, v180, v182
	s_waitcnt vmcnt(0)
	v_add_f32_e32 v184, v184, v185
	v_add_f32_e32 v186, v186, v187
	v_add_f32_e32 v184, v184, v186
	ds_bpermute_b32 v157, v204, v156
	ds_bpermute_b32 v161, v204, v160
	ds_bpermute_b32 v165, v204, v164
	ds_bpermute_b32 v169, v204, v168
	ds_bpermute_b32 v173, v204, v172
	ds_bpermute_b32 v177, v204, v176
	ds_bpermute_b32 v181, v204, v180
	ds_bpermute_b32 v185, v204, v184
	s_waitcnt lgkmcnt(0)
	v_add_f32_e32 v156, v156, v157
	v_add_f32_e32 v160, v160, v161
	v_add_f32_e32 v164, v164, v165
	v_add_f32_e32 v168, v168, v169
	v_add_f32_e32 v172, v172, v173
	v_add_f32_e32 v176, v176, v177
	v_add_f32_e32 v180, v180, v181
	v_add_f32_e32 v184, v184, v185
	s_nop 0
	ds_bpermute_b32 v157, v205, v156
	ds_bpermute_b32 v161, v205, v160
	ds_bpermute_b32 v165, v205, v164
	ds_bpermute_b32 v169, v205, v168
	ds_bpermute_b32 v173, v205, v172
	ds_bpermute_b32 v177, v205, v176
	ds_bpermute_b32 v181, v205, v180
	ds_bpermute_b32 v185, v205, v184
	s_waitcnt lgkmcnt(0)
	v_mov_b32_e32 v144, 0x358637bd
	s_mov_b32 vcc_lo, 0x3a800000
	v_add_f32_e32 v156, v156, v157
	v_add_f32_e32 v160, v160, v161
	v_add_f32_e32 v164, v164, v165
	v_add_f32_e32 v168, v168, v169
	v_add_f32_e32 v172, v172, v173
	v_add_f32_e32 v176, v176, v177
	v_add_f32_e32 v180, v180, v181
	v_add_f32_e32 v184, v184, v185
	v_fma_f32 v156, v156, vcc_lo, v144
	v_fma_f32 v160, v160, vcc_lo, v144
	v_fma_f32 v164, v164, vcc_lo, v144
	v_fma_f32 v168, v168, vcc_lo, v144
	v_fma_f32 v172, v172, vcc_lo, v144
	v_fma_f32 v176, v176, vcc_lo, v144
	v_fma_f32 v180, v180, vcc_lo, v144
	v_fma_f32 v184, v184, vcc_lo, v144
	v_rsq_f32_e32 v156, v156
	v_rsq_f32_e32 v160, v160
	v_rsq_f32_e32 v164, v164
	v_rsq_f32_e32 v168, v168
	v_rsq_f32_e32 v172, v172
	v_rsq_f32_e32 v176, v176
	v_rsq_f32_e32 v180, v180
	v_rsq_f32_e32 v184, v184
	s_nop 0
	v_mul_f32_e32 v157, 0xbfb8aa3b, v156
	v_mul_f32_e32 v161, 0xbfb8aa3b, v160
	v_mul_f32_e32 v165, 0xbfb8aa3b, v164
	v_mul_f32_e32 v169, 0xbfb8aa3b, v168
	v_mul_f32_e32 v173, 0xbfb8aa3b, v172
	v_mul_f32_e32 v177, 0xbfb8aa3b, v176
	v_mul_f32_e32 v181, 0xbfb8aa3b, v180
	v_mul_f32_e32 v185, 0xbfb8aa3b, v184
	v_mul_f32_e32 v158, v156, v156
	v_mul_f32_e32 v162, v160, v160
	v_mul_f32_e32 v166, v164, v164
	v_mul_f32_e32 v170, v168, v168
	v_mul_f32_e32 v174, v172, v172
	v_mul_f32_e32 v178, v176, v176
	v_mul_f32_e32 v182, v180, v180
	v_mul_f32_e32 v186, v184, v184
	v_mul_f32_e32 v188, v116, v157
	v_mul_f32_e32 v189, v117, v157
	v_mul_f32_e32 v190, v118, v157
	v_mul_f32_e32 v191, v119, v157
	v_mul_f32_e32 v192, v112, v157
	v_mul_f32_e32 v193, v113, v157
	v_mul_f32_e32 v194, v114, v157
	v_mul_f32_e32 v195, v115, v157
	v_exp_f32_e32 v188, v188
	v_exp_f32_e32 v189, v189
	v_exp_f32_e32 v190, v190
	v_exp_f32_e32 v191, v191
	v_exp_f32_e32 v192, v192
	v_exp_f32_e32 v193, v193
	v_exp_f32_e32 v194, v194
	v_exp_f32_e32 v195, v195
	v_mul_f32_e32 v124, v116, v124
	v_mul_f32_e32 v125, v117, v125
	v_mul_f32_e32 v126, v118, v126
	v_mul_f32_e32 v127, v119, v127
	v_mul_f32_e32 v120, v112, v120
	v_mul_f32_e32 v121, v113, v121
	v_mul_f32_e32 v122, v114, v122
	v_mul_f32_e32 v123, v115, v123
	v_add_f32_e32 v188, 1.0, v188
	v_add_f32_e32 v189, 1.0, v189
	v_add_f32_e32 v190, 1.0, v190
	v_add_f32_e32 v191, 1.0, v191
	v_add_f32_e32 v192, 1.0, v192
	v_add_f32_e32 v193, 1.0, v193
	v_add_f32_e32 v194, 1.0, v194
	v_add_f32_e32 v195, 1.0, v195
	v_rcp_f32_e32 v188, v188
	v_rcp_f32_e32 v189, v189
	v_rcp_f32_e32 v190, v190
	v_rcp_f32_e32 v191, v191
	v_rcp_f32_e32 v192, v192
	v_rcp_f32_e32 v193, v193
	v_rcp_f32_e32 v194, v194
	v_rcp_f32_e32 v195, v195
	v_mul_f32_e32 v124, v124, v158
	v_mul_f32_e32 v125, v125, v158
	v_mul_f32_e32 v126, v126, v158
	v_mul_f32_e32 v127, v127, v158
	v_mul_f32_e32 v120, v120, v158
	v_mul_f32_e32 v121, v121, v158
	v_mul_f32_e32 v122, v122, v158
	v_mul_f32_e32 v123, v123, v158
	v_mul_f32_e32 v124, v124, v188
	v_mul_f32_e32 v125, v125, v189
	v_mul_f32_e32 v126, v126, v190
	v_mul_f32_e32 v127, v127, v191
	v_mul_f32_e32 v120, v120, v192
	v_mul_f32_e32 v121, v121, v193
	v_mul_f32_e32 v122, v122, v194
	v_mul_f32_e32 v123, v123, v195
	v_cvt_pk_bf16_f32 v116, v124, v125
	v_cvt_pk_bf16_f32 v117, v126, v127
	v_cvt_pk_bf16_f32 v118, v120, v121
	v_cvt_pk_bf16_f32 v119, v122, v123
	global_store_dwordx4 v155, v[116:119], s[88:89]
	v_mul_f32_e32 v196, v104, v161
	v_mul_f32_e32 v197, v105, v161
	v_mul_f32_e32 v198, v106, v161
	v_mul_f32_e32 v199, v107, v161
	v_mul_f32_e32 v200, v100, v161
	v_mul_f32_e32 v201, v101, v161
	v_mul_f32_e32 v202, v102, v161
	v_mul_f32_e32 v203, v103, v161
	v_exp_f32_e32 v196, v196
	v_exp_f32_e32 v197, v197
	v_exp_f32_e32 v198, v198
	v_exp_f32_e32 v199, v199
	v_exp_f32_e32 v200, v200
	v_exp_f32_e32 v201, v201
	v_exp_f32_e32 v202, v202
	v_exp_f32_e32 v203, v203
	v_mul_f32_e32 v108, v104, v108
	v_mul_f32_e32 v109, v105, v109
	v_mul_f32_e32 v110, v106, v110
	v_mul_f32_e32 v111, v107, v111
	v_mul_f32_e32 v96, v100, v96
	v_mul_f32_e32 v97, v101, v97
	v_mul_f32_e32 v98, v102, v98
	v_mul_f32_e32 v99, v103, v99
	v_add_f32_e32 v196, 1.0, v196
	v_add_f32_e32 v197, 1.0, v197
	v_add_f32_e32 v198, 1.0, v198
	v_add_f32_e32 v199, 1.0, v199
	v_add_f32_e32 v200, 1.0, v200
	v_add_f32_e32 v201, 1.0, v201
	v_add_f32_e32 v202, 1.0, v202
	v_add_f32_e32 v203, 1.0, v203
	v_rcp_f32_e32 v196, v196
	v_rcp_f32_e32 v197, v197
	v_rcp_f32_e32 v198, v198
	v_rcp_f32_e32 v199, v199
	v_rcp_f32_e32 v200, v200
	v_rcp_f32_e32 v201, v201
	v_rcp_f32_e32 v202, v202
	v_rcp_f32_e32 v203, v203
	v_mul_f32_e32 v108, v108, v162
	v_mul_f32_e32 v109, v109, v162
	v_mul_f32_e32 v110, v110, v162
	v_mul_f32_e32 v111, v111, v162
	v_mul_f32_e32 v96, v96, v162
	v_mul_f32_e32 v97, v97, v162
	v_mul_f32_e32 v98, v98, v162
	v_mul_f32_e32 v99, v99, v162
	v_mul_f32_e32 v108, v108, v196
	v_mul_f32_e32 v109, v109, v197
	v_mul_f32_e32 v110, v110, v198
	v_mul_f32_e32 v111, v111, v199
	v_mul_f32_e32 v96, v96, v200
	v_mul_f32_e32 v97, v97, v201
	v_mul_f32_e32 v98, v98, v202
	v_mul_f32_e32 v99, v99, v203
	v_cvt_pk_bf16_f32 v104, v108, v109
	v_cvt_pk_bf16_f32 v105, v110, v111
	v_cvt_pk_bf16_f32 v106, v96, v97
	v_cvt_pk_bf16_f32 v107, v98, v99
	s_add_u32 s88, s88, 0x16000
	s_addc_u32 s89, s89, 0
	global_store_dwordx4 v155, v[104:107], s[88:89]
	v_mul_f32_e32 v188, v88, v165
	v_mul_f32_e32 v189, v89, v165
	v_mul_f32_e32 v190, v90, v165
	v_mul_f32_e32 v191, v91, v165
	v_mul_f32_e32 v192, v84, v165
	v_mul_f32_e32 v193, v85, v165
	v_mul_f32_e32 v194, v86, v165
	v_mul_f32_e32 v195, v87, v165
	v_exp_f32_e32 v188, v188
	v_exp_f32_e32 v189, v189
	v_exp_f32_e32 v190, v190
	v_exp_f32_e32 v191, v191
	v_exp_f32_e32 v192, v192
	v_exp_f32_e32 v193, v193
	v_exp_f32_e32 v194, v194
	v_exp_f32_e32 v195, v195
	v_mul_f32_e32 v92, v88, v92
	v_mul_f32_e32 v93, v89, v93
	v_mul_f32_e32 v94, v90, v94
	v_mul_f32_e32 v95, v91, v95
	v_mul_f32_e32 v80, v84, v80
	v_mul_f32_e32 v81, v85, v81
	v_mul_f32_e32 v82, v86, v82
	v_mul_f32_e32 v83, v87, v83
	v_add_f32_e32 v188, 1.0, v188
	v_add_f32_e32 v189, 1.0, v189
	v_add_f32_e32 v190, 1.0, v190
	v_add_f32_e32 v191, 1.0, v191
	v_add_f32_e32 v192, 1.0, v192
	v_add_f32_e32 v193, 1.0, v193
	v_add_f32_e32 v194, 1.0, v194
	v_add_f32_e32 v195, 1.0, v195
	v_rcp_f32_e32 v188, v188
	v_rcp_f32_e32 v189, v189
	v_rcp_f32_e32 v190, v190
	v_rcp_f32_e32 v191, v191
	v_rcp_f32_e32 v192, v192
	v_rcp_f32_e32 v193, v193
	v_rcp_f32_e32 v194, v194
	v_rcp_f32_e32 v195, v195
	v_mul_f32_e32 v92, v92, v166
	v_mul_f32_e32 v93, v93, v166
	v_mul_f32_e32 v94, v94, v166
	v_mul_f32_e32 v95, v95, v166
	v_mul_f32_e32 v80, v80, v166
	v_mul_f32_e32 v81, v81, v166
	v_mul_f32_e32 v82, v82, v166
	v_mul_f32_e32 v83, v83, v166
	v_mul_f32_e32 v92, v92, v188
	v_mul_f32_e32 v93, v93, v189
	v_mul_f32_e32 v94, v94, v190
	v_mul_f32_e32 v95, v95, v191
	v_mul_f32_e32 v80, v80, v192
	v_mul_f32_e32 v81, v81, v193
	v_mul_f32_e32 v82, v82, v194
	v_mul_f32_e32 v83, v83, v195
	v_cvt_pk_bf16_f32 v88, v92, v93
	v_cvt_pk_bf16_f32 v89, v94, v95
	v_cvt_pk_bf16_f32 v90, v80, v81
	v_cvt_pk_bf16_f32 v91, v82, v83
	s_add_u32 s88, s88, 0x16000
	s_addc_u32 s89, s89, 0
	global_store_dwordx4 v155, v[88:91], s[88:89]
	v_mul_f32_e32 v196, v72, v169
	v_mul_f32_e32 v197, v73, v169
	v_mul_f32_e32 v198, v74, v169
	v_mul_f32_e32 v199, v75, v169
	v_mul_f32_e32 v200, v68, v169
	v_mul_f32_e32 v201, v69, v169
	v_mul_f32_e32 v202, v70, v169
	v_mul_f32_e32 v203, v71, v169
	v_exp_f32_e32 v196, v196
	v_exp_f32_e32 v197, v197
	v_exp_f32_e32 v198, v198
	v_exp_f32_e32 v199, v199
	v_exp_f32_e32 v200, v200
	v_exp_f32_e32 v201, v201
	v_exp_f32_e32 v202, v202
	v_exp_f32_e32 v203, v203
	v_mul_f32_e32 v76, v72, v76
	v_mul_f32_e32 v77, v73, v77
	v_mul_f32_e32 v78, v74, v78
	v_mul_f32_e32 v79, v75, v79
	v_mul_f32_e32 v64, v68, v64
	v_mul_f32_e32 v65, v69, v65
	v_mul_f32_e32 v66, v70, v66
	v_mul_f32_e32 v67, v71, v67
	v_add_f32_e32 v196, 1.0, v196
	v_add_f32_e32 v197, 1.0, v197
	v_add_f32_e32 v198, 1.0, v198
	v_add_f32_e32 v199, 1.0, v199
	v_add_f32_e32 v200, 1.0, v200
	v_add_f32_e32 v201, 1.0, v201
	v_add_f32_e32 v202, 1.0, v202
	v_add_f32_e32 v203, 1.0, v203
	v_rcp_f32_e32 v196, v196
	v_rcp_f32_e32 v197, v197
	v_rcp_f32_e32 v198, v198
	v_rcp_f32_e32 v199, v199
	v_rcp_f32_e32 v200, v200
	v_rcp_f32_e32 v201, v201
	v_rcp_f32_e32 v202, v202
	v_rcp_f32_e32 v203, v203
	v_mul_f32_e32 v76, v76, v170
	v_mul_f32_e32 v77, v77, v170
	v_mul_f32_e32 v78, v78, v170
	v_mul_f32_e32 v79, v79, v170
	v_mul_f32_e32 v64, v64, v170
	v_mul_f32_e32 v65, v65, v170
	v_mul_f32_e32 v66, v66, v170
	v_mul_f32_e32 v67, v67, v170
	v_mul_f32_e32 v76, v76, v196
	v_mul_f32_e32 v77, v77, v197
	v_mul_f32_e32 v78, v78, v198
	v_mul_f32_e32 v79, v79, v199
	v_mul_f32_e32 v64, v64, v200
	v_mul_f32_e32 v65, v65, v201
	v_mul_f32_e32 v66, v66, v202
	v_mul_f32_e32 v67, v67, v203
	v_cvt_pk_bf16_f32 v72, v76, v77
	v_cvt_pk_bf16_f32 v73, v78, v79
	v_cvt_pk_bf16_f32 v74, v64, v65
	v_cvt_pk_bf16_f32 v75, v66, v67
	s_add_u32 s88, s88, 0x16000
	s_addc_u32 s89, s89, 0
	global_store_dwordx4 v155, v[72:75], s[88:89]
	v_mul_f32_e32 v188, v56, v173
	v_mul_f32_e32 v189, v57, v173
	v_mul_f32_e32 v190, v58, v173
	v_mul_f32_e32 v191, v59, v173
	v_mul_f32_e32 v192, v52, v173
	v_mul_f32_e32 v193, v53, v173
	v_mul_f32_e32 v194, v54, v173
	v_mul_f32_e32 v195, v55, v173
	v_exp_f32_e32 v188, v188
	v_exp_f32_e32 v189, v189
	v_exp_f32_e32 v190, v190
	v_exp_f32_e32 v191, v191
	v_exp_f32_e32 v192, v192
	v_exp_f32_e32 v193, v193
	v_exp_f32_e32 v194, v194
	v_exp_f32_e32 v195, v195
	v_mul_f32_e32 v60, v56, v60
	v_mul_f32_e32 v61, v57, v61
	v_mul_f32_e32 v62, v58, v62
	v_mul_f32_e32 v63, v59, v63
	v_mul_f32_e32 v48, v52, v48
	v_mul_f32_e32 v49, v53, v49
	v_mul_f32_e32 v50, v54, v50
	v_mul_f32_e32 v51, v55, v51
	v_add_f32_e32 v188, 1.0, v188
	v_add_f32_e32 v189, 1.0, v189
	v_add_f32_e32 v190, 1.0, v190
	v_add_f32_e32 v191, 1.0, v191
	v_add_f32_e32 v192, 1.0, v192
	v_add_f32_e32 v193, 1.0, v193
	v_add_f32_e32 v194, 1.0, v194
	v_add_f32_e32 v195, 1.0, v195
	v_rcp_f32_e32 v188, v188
	v_rcp_f32_e32 v189, v189
	v_rcp_f32_e32 v190, v190
	v_rcp_f32_e32 v191, v191
	v_rcp_f32_e32 v192, v192
	v_rcp_f32_e32 v193, v193
	v_rcp_f32_e32 v194, v194
	v_rcp_f32_e32 v195, v195
	v_mul_f32_e32 v60, v60, v174
	v_mul_f32_e32 v61, v61, v174
	v_mul_f32_e32 v62, v62, v174
	v_mul_f32_e32 v63, v63, v174
	v_mul_f32_e32 v48, v48, v174
	v_mul_f32_e32 v49, v49, v174
	v_mul_f32_e32 v50, v50, v174
	v_mul_f32_e32 v51, v51, v174
	v_mul_f32_e32 v60, v60, v188
	v_mul_f32_e32 v61, v61, v189
	v_mul_f32_e32 v62, v62, v190
	v_mul_f32_e32 v63, v63, v191
	v_mul_f32_e32 v48, v48, v192
	v_mul_f32_e32 v49, v49, v193
	v_mul_f32_e32 v50, v50, v194
	v_mul_f32_e32 v51, v51, v195
	v_cvt_pk_bf16_f32 v56, v60, v61
	v_cvt_pk_bf16_f32 v57, v62, v63
	v_cvt_pk_bf16_f32 v58, v48, v49
	v_cvt_pk_bf16_f32 v59, v50, v51
	s_add_u32 s88, s88, 0x6e000
	s_addc_u32 s89, s89, 0
	global_store_dwordx4 v155, v[56:59], s[88:89]
	v_mul_f32_e32 v196, v40, v177
	v_mul_f32_e32 v197, v41, v177
	v_mul_f32_e32 v198, v42, v177
	v_mul_f32_e32 v199, v43, v177
	v_mul_f32_e32 v200, v36, v177
	v_mul_f32_e32 v201, v37, v177
	v_mul_f32_e32 v202, v38, v177
	v_mul_f32_e32 v203, v39, v177
	v_exp_f32_e32 v196, v196
	v_exp_f32_e32 v197, v197
	v_exp_f32_e32 v198, v198
	v_exp_f32_e32 v199, v199
	v_exp_f32_e32 v200, v200
	v_exp_f32_e32 v201, v201
	v_exp_f32_e32 v202, v202
	v_exp_f32_e32 v203, v203
	v_mul_f32_e32 v44, v40, v44
	v_mul_f32_e32 v45, v41, v45
	v_mul_f32_e32 v46, v42, v46
	v_mul_f32_e32 v47, v43, v47
	v_mul_f32_e32 v32, v36, v32
	v_mul_f32_e32 v33, v37, v33
	v_mul_f32_e32 v34, v38, v34
	v_mul_f32_e32 v35, v39, v35
	v_add_f32_e32 v196, 1.0, v196
	v_add_f32_e32 v197, 1.0, v197
	v_add_f32_e32 v198, 1.0, v198
	v_add_f32_e32 v199, 1.0, v199
	v_add_f32_e32 v200, 1.0, v200
	v_add_f32_e32 v201, 1.0, v201
	v_add_f32_e32 v202, 1.0, v202
	v_add_f32_e32 v203, 1.0, v203
	v_rcp_f32_e32 v196, v196
	v_rcp_f32_e32 v197, v197
	v_rcp_f32_e32 v198, v198
	v_rcp_f32_e32 v199, v199
	v_rcp_f32_e32 v200, v200
	v_rcp_f32_e32 v201, v201
	v_rcp_f32_e32 v202, v202
	v_rcp_f32_e32 v203, v203
	v_mul_f32_e32 v44, v44, v178
	v_mul_f32_e32 v45, v45, v178
	v_mul_f32_e32 v46, v46, v178
	v_mul_f32_e32 v47, v47, v178
	v_mul_f32_e32 v32, v32, v178
	v_mul_f32_e32 v33, v33, v178
	v_mul_f32_e32 v34, v34, v178
	v_mul_f32_e32 v35, v35, v178
	v_mul_f32_e32 v44, v44, v196
	v_mul_f32_e32 v45, v45, v197
	v_mul_f32_e32 v46, v46, v198
	v_mul_f32_e32 v47, v47, v199
	v_mul_f32_e32 v32, v32, v200
	v_mul_f32_e32 v33, v33, v201
	v_mul_f32_e32 v34, v34, v202
	v_mul_f32_e32 v35, v35, v203
	v_cvt_pk_bf16_f32 v40, v44, v45
	v_cvt_pk_bf16_f32 v41, v46, v47
	v_cvt_pk_bf16_f32 v42, v32, v33
	v_cvt_pk_bf16_f32 v43, v34, v35
	s_add_u32 s88, s88, 0x16000
	s_addc_u32 s89, s89, 0
	global_store_dwordx4 v155, v[40:43], s[88:89]
	v_mul_f32_e32 v188, v24, v181
	v_mul_f32_e32 v189, v25, v181
	v_mul_f32_e32 v190, v26, v181
	v_mul_f32_e32 v191, v27, v181
	v_mul_f32_e32 v192, v20, v181
	v_mul_f32_e32 v193, v21, v181
	v_mul_f32_e32 v194, v22, v181
	v_mul_f32_e32 v195, v23, v181
	v_exp_f32_e32 v188, v188
	v_exp_f32_e32 v189, v189
	v_exp_f32_e32 v190, v190
	v_exp_f32_e32 v191, v191
	v_exp_f32_e32 v192, v192
	v_exp_f32_e32 v193, v193
	v_exp_f32_e32 v194, v194
	v_exp_f32_e32 v195, v195
	v_mul_f32_e32 v28, v24, v28
	v_mul_f32_e32 v29, v25, v29
	v_mul_f32_e32 v30, v26, v30
	v_mul_f32_e32 v31, v27, v31
	v_mul_f32_e32 v16, v20, v16
	v_mul_f32_e32 v17, v21, v17
	v_mul_f32_e32 v18, v22, v18
	v_mul_f32_e32 v19, v23, v19
	v_add_f32_e32 v188, 1.0, v188
	v_add_f32_e32 v189, 1.0, v189
	v_add_f32_e32 v190, 1.0, v190
	v_add_f32_e32 v191, 1.0, v191
	v_add_f32_e32 v192, 1.0, v192
	v_add_f32_e32 v193, 1.0, v193
	v_add_f32_e32 v194, 1.0, v194
	v_add_f32_e32 v195, 1.0, v195
	v_rcp_f32_e32 v188, v188
	v_rcp_f32_e32 v189, v189
	v_rcp_f32_e32 v190, v190
	v_rcp_f32_e32 v191, v191
	v_rcp_f32_e32 v192, v192
	v_rcp_f32_e32 v193, v193
	v_rcp_f32_e32 v194, v194
	v_rcp_f32_e32 v195, v195
	v_mul_f32_e32 v28, v28, v182
	v_mul_f32_e32 v29, v29, v182
	v_mul_f32_e32 v30, v30, v182
	v_mul_f32_e32 v31, v31, v182
	v_mul_f32_e32 v16, v16, v182
	v_mul_f32_e32 v17, v17, v182
	v_mul_f32_e32 v18, v18, v182
	v_mul_f32_e32 v19, v19, v182
	v_mul_f32_e32 v28, v28, v188
	v_mul_f32_e32 v29, v29, v189
	v_mul_f32_e32 v30, v30, v190
	v_mul_f32_e32 v31, v31, v191
	v_mul_f32_e32 v16, v16, v192
	v_mul_f32_e32 v17, v17, v193
	v_mul_f32_e32 v18, v18, v194
	v_mul_f32_e32 v19, v19, v195
	v_cvt_pk_bf16_f32 v24, v28, v29
	v_cvt_pk_bf16_f32 v25, v30, v31
	v_cvt_pk_bf16_f32 v26, v16, v17
	v_cvt_pk_bf16_f32 v27, v18, v19
	s_add_u32 s88, s88, 0x16000
	s_addc_u32 s89, s89, 0
	global_store_dwordx4 v155, v[24:27], s[88:89]
	v_mul_f32_e32 v196, v8, v185
	v_mul_f32_e32 v197, v9, v185
	v_mul_f32_e32 v198, v10, v185
	v_mul_f32_e32 v199, v11, v185
	v_mul_f32_e32 v200, v4, v185
	v_mul_f32_e32 v201, v5, v185
	v_mul_f32_e32 v202, v6, v185
	v_mul_f32_e32 v203, v7, v185
	v_exp_f32_e32 v196, v196
	v_exp_f32_e32 v197, v197
	v_exp_f32_e32 v198, v198
	v_exp_f32_e32 v199, v199
	v_exp_f32_e32 v200, v200
	v_exp_f32_e32 v201, v201
	v_exp_f32_e32 v202, v202
	v_exp_f32_e32 v203, v203
	v_mul_f32_e32 v12, v8, v12
	v_mul_f32_e32 v13, v9, v13
	v_mul_f32_e32 v14, v10, v14
	v_mul_f32_e32 v15, v11, v15
	v_mul_f32_e32 v0, v4, v0
	v_mul_f32_e32 v1, v5, v1
	v_mul_f32_e32 v2, v6, v2
	v_mul_f32_e32 v3, v7, v3
	v_add_f32_e32 v196, 1.0, v196
	v_add_f32_e32 v197, 1.0, v197
	v_add_f32_e32 v198, 1.0, v198
	v_add_f32_e32 v199, 1.0, v199
	v_add_f32_e32 v200, 1.0, v200
	v_add_f32_e32 v201, 1.0, v201
	v_add_f32_e32 v202, 1.0, v202
	v_add_f32_e32 v203, 1.0, v203
	v_rcp_f32_e32 v196, v196
	v_rcp_f32_e32 v197, v197
	v_rcp_f32_e32 v198, v198
	v_rcp_f32_e32 v199, v199
	v_rcp_f32_e32 v200, v200
	v_rcp_f32_e32 v201, v201
	v_rcp_f32_e32 v202, v202
	v_rcp_f32_e32 v203, v203
	v_mul_f32_e32 v12, v12, v186
	v_mul_f32_e32 v13, v13, v186
	v_mul_f32_e32 v14, v14, v186
	v_mul_f32_e32 v15, v15, v186
	v_mul_f32_e32 v0, v0, v186
	v_mul_f32_e32 v1, v1, v186
	v_mul_f32_e32 v2, v2, v186
	v_mul_f32_e32 v3, v3, v186
	v_mul_f32_e32 v12, v12, v196
	v_mul_f32_e32 v13, v13, v197
	v_mul_f32_e32 v14, v14, v198
	v_mul_f32_e32 v15, v15, v199
	v_mul_f32_e32 v0, v0, v200
	v_mul_f32_e32 v1, v1, v201
	v_mul_f32_e32 v2, v2, v202
	v_mul_f32_e32 v3, v3, v203
	v_cvt_pk_bf16_f32 v8, v12, v13
	v_cvt_pk_bf16_f32 v9, v14, v15
	v_cvt_pk_bf16_f32 v10, v0, v1
	v_cvt_pk_bf16_f32 v11, v2, v3
	s_add_u32 s88, s88, 0x16000
	s_addc_u32 s89, s89, 0
	global_store_dwordx4 v155, v[8:11], s[88:89]
	s_andn2_b64 vcc, exec, s[8:9]
	s_mov_b64 s[8:9], -1
	s_cbranch_vccnz .LBB0_1399
	s_andn2_b64 vcc, exec, s[10:11]
	s_cbranch_vccnz .LBB0_1398
	s_barrier
	s_branch .LBB0_1398
